# counted vmcnt waits in EpiRes epilogues + conflict-free LDS swizzle for attention K/rope reads
# speedup vs baseline: 1.0043x; 1.0043x over previous
.LBB0_560:
	s_ashr_i32 s0, s4, 3
	s_and_b32 s14, s4, 7
	s_ashr_i32 s1, s0, 31
	s_lshl_b32 s4, s5, 8
	s_lshl_b64 s[46:47], s[0:1], 12
	s_and_b32 s4, s4, 0xf00
	s_or_b32 s46, s46, s4
	s_mul_i32 s4, s47, 0xc00
	s_mul_hi_u32 s5, s46, 0xc00
	s_add_i32 s5, s5, s4
	s_mul_i32 s4, s46, 0xc00
	s_add_u32 s6, s48, s4
	s_addc_u32 s7, s49, s5
	s_lshl_b32 s13, s14, 7
	s_lshl_b32 s4, s14, 8
	s_add_u32 s4, s6, s4
	s_addc_u32 s5, s7, 0
	s_barrier
	s_add_u32 s6, s6, s13
	v_mbcnt_lo_u32_b32 v60, -1, 0
	v_mbcnt_hi_u32_b32 v60, -1, v60
	s_addc_u32 s7, s7, 0
	v_or_b32_e32 v34, s33, v60
	v_ashrrev_i32_e32 v61, 1, v34
	s_movk_i32 s15, 0xffe0
	v_bfe_u32 v176, v60, 5, 1
	v_bfi_b32 v48, s15, v61, v60
	v_mov_b64_e32 v[0:1], s[6:7]
	v_lshlrev_b32_e32 v160, 4, v176
	v_mad_i64_i32 v[0:1], s[6:7], v48, s91, v[0:1]
	v_lshl_add_u64 v[12:13], v[0:1], 0, v[160:161]
	global_load_dwordx4 v[0:3], v[12:13], off offset:2048
	global_load_dwordx4 v[4:7], v[12:13], off offset:2080
	global_load_dwordx4 v[8:11], v[12:13], off offset:2112
	s_nop 0
	global_load_dwordx4 v[12:15], v[12:13], off offset:2144
	s_lshl_b64 s[6:7], s[0:1], 24
	s_add_u32 s16, s50, s6
	v_ashrrev_i32_e32 v36, 4, v34
	s_addc_u32 s17, s51, s7
	s_lshl_b32 s15, s14, 9
	v_add_u32_e32 v40, 32, v36
	s_add_u32 s16, s16, s15
	v_lshlrev_b32_e32 v49, 3, v34
	v_ashrrev_i32_e32 v37, 31, v36
	v_ashrrev_i32_e32 v41, 31, v40
	s_addc_u32 s17, s17, 0
	v_and_b32_e32 v16, 0x78, v49
	v_lshlrev_b64 v[52:53], 12, v[36:37]
	v_lshlrev_b64 v[20:21], 12, v[40:41]
	s_lshl_b64 s[0:1], s[0:1], 19
	v_ashrrev_i32_e32 v42, 3, v34
	v_lshlrev_b32_e32 v38, 1, v16
	v_lshl_add_u64 v[16:17], s[16:17], 0, v[52:53]
	v_lshl_add_u64 v[20:21], s[16:17], 0, v[20:21]
	s_add_u32 s16, s8, s0
	v_ashrrev_i32_e32 v43, 31, v42
	s_addc_u32 s17, s9, s1
	v_lshlrev_b64 v[54:55], 7, v[42:43]
	v_lshlrev_b32_e32 v34, 4, v34
	v_mov_b32_e32 v39, v161
	v_lshl_add_u64 v[32:33], s[16:17], 0, v[54:55]
	v_and_b32_e32 v44, 0x70, v34
	v_mov_b32_e32 v45, v161
	v_lshl_add_u64 v[56:57], v[16:17], 0, v[38:39]
	v_lshl_add_u64 v[28:29], v[20:21], 0, v[38:39]
	v_lshl_add_u64 v[58:59], v[32:33], 0, v[44:45]
	global_load_dwordx4 v[16:19], v[56:57], off offset:256
	global_load_dwordx4 v[24:27], v[56:57], off
	global_load_dwordx4 v[20:23], v[28:29], off offset:256
	global_load_dwordx4 v[32:35], v[58:59], off
	v_mov_b64_e32 v[46:47], s[4:5]
	global_load_dwordx4 v[28:31], v[28:29], off
	v_mad_i64_i32 v[46:47], s[4:5], v48, s91, v[46:47]
	v_lshl_add_u64 v[46:47], v[46:47], 0, v[160:161]
	global_load_dwordx4 v[120:123], v[46:47], off
	global_load_dwordx4 v[124:127], v[46:47], off offset:32
	global_load_dwordx4 v[116:119], v[46:47], off offset:64
	global_load_dwordx4 v[112:115], v[46:47], off offset:96
	global_load_dwordx4 v[108:111], v[46:47], off offset:128
	global_load_dwordx4 v[104:107], v[46:47], off offset:160
	global_load_dwordx4 v[100:103], v[46:47], off offset:192
	global_load_dwordx4 v[96:99], v[46:47], off offset:224
	v_lshlrev_b32_e32 v63, 4, v60
	s_add_i32 s5, 0, 0x14800
	v_and_b32_e32 v64, 0x70, v63
	v_and_b32_e32 v240, 0xf0, v63
	v_lshlrev_b32_e32 v241, 3, v60
	v_and_b32_e32 v241, 0x70, v241
	v_lshrrev_b32_e32 v242, 1, v60
	v_bitop3_b32 v37, v176, v242, 7 bitop3:0x78
	v_lshl_add_u32 v65, v48, 7, s5
	v_bitop3_b32 v39, v160, v241, 32 bitop3:0x36
	v_lshl_add_u32 v37, v37, 4, v65
	v_add_u32_e32 v184, v65, v39
	s_movk_i32 s5, 0x60
	v_mov_b32_e32 v62, s33
	s_movk_i32 s14, 0x70
	s_add_i32 s4, 0, 0x14000
	s_cmp_lg_u32 0, -1
	v_and_b32_e32 v177, 31, v60
	s_cselect_b32 s16, 0, 0
	v_or_b32_e32 v66, 64, v160
	v_or_b32_e32 v67, 0x60, v160
	s_waitcnt vmcnt(16)
	ds_write_b128 v37, v[0:3]
	s_waitcnt vmcnt(15)
	ds_write_b128 v184, v[4:7]
	v_bitop3_b32 v0, v160, v241, 64 bitop3:0x36
	v_add_u32_e32 v183, v65, v0
	v_bitop3_b32 v0, v160, v241, s5 bitop3:0x36
	v_add_u32_e32 v182, v65, v0
	v_and_b32_e32 v0, 0xfffff0, v36
	v_lshlrev_b32_e32 v1, 1, v36
	v_and_b32_e32 v4, 0xfffff0, v40
	v_lshlrev_b32_e32 v5, 1, v40
	v_and_or_b32 v0, v1, 8, v0
	v_and_or_b32 v4, v5, 8, v4
	v_lshrrev_b32_e32 v1, 1, v36
	v_lshrrev_b32_e32 v0, 1, v0
	v_bfe_u32 v2, v49, 5, 2
	v_and_b32_e32 v3, 3, v36
	v_lshrrev_b32_e32 v4, 1, v4
	v_or_b32_e32 v0, v0, v2
	v_and_or_b32 v1, v1, 4, v3
	v_or_b32_e32 v2, v4, v2
	v_lshlrev_b32_e32 v0, 9, v0
	v_lshlrev_b32_e32 v1, 6, v1
	v_and_b32_e32 v3, 48, v38
	v_lshlrev_b32_e32 v2, 9, v2
	v_or3_b32 v0, v0, v1, v3
	v_or3_b32 v1, v2, v1, v3
	v_add_u32_e32 v185, 0, v0
	v_add_u32_e32 v186, 0, v1
	v_lshlrev_b32_e32 v0, 8, v36
	v_bitop3_b32 v1, v60, s14, v62 bitop3:0xc8
	v_or_b32_e32 v243, s33, v60
	v_and_b32_e32 v243, 0xf0, v243
	v_bitop3_b32 v0, v38, v0, v243 bitop3:0xde
	v_add_u32_e32 v187, 0, v0
	v_lshlrev_b32_e32 v0, 8, v40
	v_bitop3_b32 v0, v38, v0, v243 bitop3:0xde
	v_lshlrev_b32_e32 v1, 3, v42
	v_add_u32_e32 v188, 0, v0
	v_lshlrev_b32_e32 v0, 7, v42
	v_and_b32_e32 v1, 0x70, v1
	v_bitop3_b32 v75, v44, v0, v1 bitop3:0xde
	s_add_i32 s5, 0, 0x10000
	s_waitcnt vmcnt(14)
	ds_write_b128 v183, v[8:11]
	s_waitcnt vmcnt(13)
	ds_write_b128 v182, v[12:15]
	v_add_u32_e32 v0, s5, v75
	v_lshlrev_b32_e32 v8, 8, v177
	s_waitcnt vmcnt(0)
	s_waitcnt vmcnt(12)
	ds_write_b128 v185, v[16:19]
	s_waitcnt vmcnt(10)
	ds_write_b128 v186, v[20:23]
	ds_write_b128 v187, v[24:27] offset:32768
	s_waitcnt vmcnt(8)
	ds_write_b128 v188, v[28:31] offset:32768
	ds_write_b128 v0, v[32:35]
	v_bitop3_b32 v0, v160, v8, v240 bitop3:0xde
	v_add_u32_e32 v189, 0, v0
	s_waitcnt lgkmcnt(0)
	s_barrier
	ds_read_b128 v[0:3], v189 offset:32768
	ds_read_b128 v[48:51], v182
	v_or_b32_e32 v12, 32, v160
	v_bitop3_b32 v4, v12, v8, v240 bitop3:0xde
	v_add_u32_e32 v190, 0, v4
	s_waitcnt vmcnt(7) lgkmcnt(1)
	v_mfma_f32_32x32x16_bf16 v[32:47], v[0:3], v[120:123], 0
	ds_read_b128 v[0:3], v189 offset:40960
	ds_read_b128 v[4:7], v190 offset:32768
	v_lshlrev_b32_e32 v68, 7, v177
	v_bitop3_b32 v198, v160, v68, v241 bitop3:0xde
	v_add_u32_e32 v199, s5, v198
	v_bitop3_b32 v200, v12, v68, v241 bitop3:0xde
	v_add_u32_e32 v201, s5, v200
	s_waitcnt vmcnt(6) lgkmcnt(0)
	v_mfma_f32_32x32x16_bf16 v[32:47], v[4:7], v[124:127], v[32:47]
	v_bitop3_b32 v4, v66, v8, v240 bitop3:0xde
	v_add_u32_e32 v191, 0, v4
	ds_read_b128 v[4:7], v191 offset:32768
	v_bitop3_b32 v202, v66, v68, v241 bitop3:0xde
	v_add_u32_e32 v203, s5, v202
	v_and_b32_e32 v76, 63, v60
	v_and_b32_e32 v156, 0xffffffe0, v61
	v_mfma_f32_32x32x16_bf16 v[16:31], v[0:3], v[120:123], 0
	ds_read_b128 v[0:3], v190 offset:40960
	v_lshlrev_b32_e32 v61, 3, v76
	v_bitop3_b32 v204, v67, v68, v241 bitop3:0xde
	v_add_u32_e32 v205, s5, v204
	v_readlane_b32 s68, v254, 50
	v_readlane_b32 s69, v254, 51
	s_mov_b32 s5, s69
	s_waitcnt vmcnt(5) lgkmcnt(1)
	v_mfma_f32_32x32x16_bf16 v[32:47], v[4:7], v[116:119], v[32:47]
	v_bitop3_b32 v4, v67, v8, v240 bitop3:0xde
	v_add_u32_e32 v192, 0, v4
	ds_read_b128 v[4:7], v192 offset:32768
	v_readlane_b32 s70, v254, 52
	v_readlane_b32 s71, v254, 53
	v_readlane_b32 s72, v254, 54
	v_readlane_b32 s73, v254, 55
	s_waitcnt lgkmcnt(1)
	v_mfma_f32_32x32x16_bf16 v[16:31], v[0:3], v[124:127], v[16:31]
	ds_read_b128 v[0:3], v191 offset:40960
	v_readlane_b32 s74, v254, 56
	v_readlane_b32 s75, v254, 57
	v_readlane_b32 s76, v254, 58
	v_readlane_b32 s77, v254, 59
	v_readlane_b32 s78, v254, 60
	v_readlane_b32 s79, v254, 61
	s_waitcnt vmcnt(4) lgkmcnt(1)
	v_mfma_f32_32x32x16_bf16 v[32:47], v[4:7], v[112:115], v[32:47]
	v_or_b32_e32 v4, 0x80, v160
	v_bitop3_b32 v4, v4, v8, v240 bitop3:0xde
	v_add_u32_e32 v193, 0, v4
	ds_read_b128 v[4:7], v193 offset:32768
	v_readlane_b32 s80, v254, 62
	v_readlane_b32 s81, v254, 63
	v_readlane_b32 s82, v255, 0
	s_waitcnt lgkmcnt(1)
	v_mfma_f32_32x32x16_bf16 v[16:31], v[0:3], v[116:119], v[16:31]
	ds_read_b128 v[0:3], v192 offset:40960
	v_readlane_b32 s83, v255, 1
	v_add_co_u32_e32 v66, vcc, s89, v56
	v_mov_b32_e32 v78, 0xf149f2ca
	s_nop 0
	v_addc_co_u32_e32 v67, vcc, 0, v57, vcc
	s_waitcnt vmcnt(3) lgkmcnt(1)
	v_mfma_f32_32x32x16_bf16 v[32:47], v[4:7], v[108:111], v[32:47]
	v_or_b32_e32 v4, 0xa0, v160
	v_bitop3_b32 v4, v4, v8, v240 bitop3:0xde
	v_add_u32_e32 v194, 0, v4
	ds_read_b128 v[4:7], v194 offset:32768
	s_mov_b32 s68, s69
	s_mov_b32 s70, s69
	s_mov_b32 s71, s69
	s_waitcnt lgkmcnt(1)
	v_mfma_f32_32x32x16_bf16 v[16:31], v[0:3], v[112:115], v[16:31]
	ds_read_b128 v[0:3], v193 offset:40960
	s_mov_b32 s72, s69
	s_mov_b32 s73, s69
	s_mov_b32 s74, s69
	s_mov_b32 s75, s69
	s_mov_b32 s76, s69
	s_mov_b32 s77, s69
	s_waitcnt lgkmcnt(0)
	v_mfma_f32_32x32x16_bf16 v[16:31], v[0:3], v[108:111], v[16:31]
	ds_read_b128 v[0:3], v194 offset:40960
	s_mov_b32 s78, s69
	s_mov_b32 s79, s69
	s_mov_b32 s80, s69
	s_mov_b32 s81, s69
	s_mov_b32 s82, s69
	s_mov_b32 s83, s69
	s_waitcnt vmcnt(2)
	v_mfma_f32_32x32x16_bf16 v[32:47], v[4:7], v[104:107], v[32:47]
	v_or_b32_e32 v4, 0xc0, v160
	v_bitop3_b32 v4, v4, v8, v240 bitop3:0xde
	v_add_u32_e32 v195, 0, v4
	ds_read_b128 v[4:7], v195 offset:32768
	v_add_u32_e32 v207, 0, v75
	v_add_u32_e32 v208, 0x12000, v207
	v_lshl_add_u64 v[170:171], s[0:1], 0, v[54:55]
	s_waitcnt lgkmcnt(1)
	v_mfma_f32_32x32x16_bf16 v[16:31], v[0:3], v[104:107], v[16:31]
	ds_read_b128 v[0:3], v195 offset:40960
	v_mov_b32_e32 v179, 0
	s_waitcnt vmcnt(1) lgkmcnt(1)
	v_mfma_f32_32x32x16_bf16 v[32:47], v[4:7], v[100:103], v[32:47]
	v_or_b32_e32 v4, 0xe0, v160
	v_bitop3_b32 v4, v4, v8, v240 bitop3:0xde
	v_add_u32_e32 v196, 0, v4
	ds_read_b128 v[4:7], v196 offset:32768
	s_waitcnt lgkmcnt(1)
	v_mfma_f32_32x32x16_bf16 v[16:31], v[0:3], v[100:103], v[16:31]
	ds_read_b128 v[0:3], v196 offset:40960
	s_waitcnt vmcnt(0) lgkmcnt(1)
	v_mfma_f32_32x32x16_bf16 v[32:47], v[4:7], v[96:99], v[32:47]
	ds_read_b128 v[4:7], v199
	s_waitcnt lgkmcnt(1)
	v_mfma_f32_32x32x16_bf16 v[16:31], v[0:3], v[96:99], v[16:31]
	v_xor_b32_e32 v0, v160, v241
	v_add_u32_e32 v197, v65, v0
	ds_read_b128 v[0:3], v197
	ds_read_b128 v[8:11], v199 offset:4096
	s_mov_b32 s14, 0x3fffffc0
	v_bitop3_b32 v62, v60, s14, v62 bitop3:0xc8
	v_lshl_add_u32 v157, v62, 2, s4
	v_and_b32_e32 v62, 0xc0, v63
	s_waitcnt lgkmcnt(1)
	v_mfma_f32_32x32x16_bf16 v[32:47], v[4:7], v[0:3], v[32:47]
	s_mov_b32 s14, -1
	v_lshl_add_u32 v178, v177, 2, v157
	s_waitcnt lgkmcnt(0)
	v_mfma_f32_32x32x16_bf16 v[16:31], v[8:11], v[0:3], v[16:31]
	ds_read_b128 v[0:3], v201
	ds_read_b128 v[4:7], v184
	ds_read_b128 v[8:11], v201 offset:4096
	ds_read_b128 v[12:15], v183
	s_waitcnt lgkmcnt(2)
	v_mfma_f32_32x32x16_bf16 v[32:47], v[0:3], v[4:7], v[32:47]
	ds_read_b128 v[0:3], v203
	s_waitcnt lgkmcnt(2)
	v_mfma_f32_32x32x16_bf16 v[16:31], v[8:11], v[4:7], v[16:31]
	v_lshlrev_b32_e32 v5, 1, v60
	v_and_or_b32 v4, v61, 24, v62
	v_and_b32_e32 v5, 32, v5
	v_and_b32_e32 v6, 0x100, v61
	v_or3_b32 v61, v4, v5, v6
	ds_read_b128 v[4:7], v203 offset:4096
	ds_read_b128 v[62:65], v205 offset:4096
	s_waitcnt lgkmcnt(2)
	v_mfma_f32_32x32x16_bf16 v[32:47], v[0:3], v[12:15], v[32:47]
	ds_read_b128 v[0:3], v205
	v_add_u32_e32 v181, s16, v61
	v_writelane_b32 v254, s4, 50
	s_nop 1
	v_writelane_b32 v255, s18, 0
	v_writelane_b32 v254, s5, 51
	s_waitcnt lgkmcnt(2)
	v_mfma_f32_32x32x16_bf16 v[16:31], v[4:7], v[12:15], v[16:31]
	v_writelane_b32 v255, s19, 1
	s_mov_b64 s[4:5], 0x40000
	v_writelane_b32 v254, s6, 52
	v_writelane_b32 v254, s7, 53
	v_writelane_b32 v254, s8, 54
	v_writelane_b32 v254, s9, 55
	v_writelane_b32 v254, s10, 56
	s_waitcnt lgkmcnt(0)
	v_mfma_f32_32x32x16_bf16 v[32:47], v[0:3], v[48:51], v[32:47]
	v_writelane_b32 v254, s11, 57
	v_writelane_b32 v254, s12, 58
	v_writelane_b32 v254, s13, 59
	v_writelane_b32 v254, s14, 60
	v_writelane_b32 v254, s15, 61
	v_mov_b64_e32 v[0:1], s[68:69]
	v_lshl_add_u64 v[158:159], s[6:7], 0, v[52:53]
	v_mfma_f32_32x32x16_bf16 v[16:31], v[62:65], v[48:51], v[16:31]
	s_nop 3
	v_max_f32_e32 v48, v33, v33
	v_max_f32_e32 v49, v32, v32
	v_max_f32_e32 v48, v49, v48
	v_max3_f32 v74, v48, v34, v35
	v_lshl_add_u64 v[48:49], v[56:57], 0, s[4:5]
	s_mov_b64 s[4:5], 0x60000
	v_lshl_add_u64 v[62:63], v[56:57], 0, s[4:5]
	s_mov_b32 s4, 0x60000
	v_add_co_u32_e32 v56, vcc, s4, v56
	global_load_dwordx4 v[48:51], v[48:49], off offset:256
	s_nop 0
	global_load_dwordx4 v[62:65], v[62:63], off offset:256
	v_addc_co_u32_e32 v57, vcc, 0, v57, vcc
	global_load_dwordx4 v[66:69], v[66:67], off
	s_nop 0
	global_load_dwordx4 v[70:73], v[56:57], off
	v_add_co_u32_e32 v56, vcc, s63, v58
	v_max3_f32 v74, v74, v36, v37
	s_nop 0
	v_addc_co_u32_e32 v57, vcc, 0, v59, vcc
	global_load_dwordx4 v[56:59], v[56:57], off
	v_max3_f32 v74, v74, v38, v39
	v_max3_f32 v74, v74, v40, v41
	v_max3_f32 v74, v74, v42, v43
	v_max3_f32 v74, v74, v44, v45
	v_max3_f32 v74, v74, v46, v47
	v_max3_f32 v74, v74, v16, v17
	v_max3_f32 v74, v74, v18, v19
	v_max3_f32 v74, v74, v20, v21
	v_max3_f32 v74, v74, v22, v23
	v_max3_f32 v74, v74, v24, v25
	v_max3_f32 v74, v74, v26, v27
	v_max3_f32 v74, v74, v28, v29
	v_max3_f32 v74, v74, v30, v31
	v_mov_b32_e32 v77, v74
	s_nop 1
	v_permlane32_swap_b32_e32 v74, v77
	v_max_f32_e32 v77, v77, v77
	v_max_f32_e32 v74, v74, v74
	v_max_f32_e32 v74, v74, v77
	v_add_f32_e32 v77, 0x7149f2ca, v74
	v_max_f32_e32 v74, 0xf149f2ca, v74
	v_cmp_ge_f32_e32 vcc, s90, v77
	v_sub_f32_e32 v77, 0xf149f2ca, v74
	v_mul_f32_e32 v77, 0x3dd53b94, v77
	v_exp_f32_e32 v77, v77
	s_cmp_eq_u64 vcc, exec
	s_cselect_b64 vcc, -1, 0
	v_cndmask_b32_e32 v209, v74, v78, vcc
	v_mul_f32_e32 v74, 0xbdd53b94, v209
	v_cndmask_b32_e64 v206, v77, 1.0, vcc
	v_mov_b32_e32 v77, v74
	v_fmamk_f32 v32, v32, 0x3dd53b94, v74
	v_fmamk_f32 v33, v33, 0x3dd53b94, v74
	v_fmamk_f32 v34, v34, 0x3dd53b94, v74
	v_fmamk_f32 v35, v35, 0x3dd53b94, v74
	v_fmamk_f32 v36, v36, 0x3dd53b94, v74
	v_fmamk_f32 v37, v37, 0x3dd53b94, v74
	v_fmamk_f32 v38, v38, 0x3dd53b94, v74
	v_fmamk_f32 v39, v39, 0x3dd53b94, v74
	v_fmamk_f32 v40, v40, 0x3dd53b94, v74
	v_fmamk_f32 v41, v41, 0x3dd53b94, v74
	v_fmamk_f32 v42, v42, 0x3dd53b94, v74
	v_fmamk_f32 v43, v43, 0x3dd53b94, v74
	v_fmamk_f32 v44, v44, 0x3dd53b94, v74
	v_fmamk_f32 v45, v45, 0x3dd53b94, v74
	v_fmamk_f32 v46, v46, 0x3dd53b94, v74
	v_fmac_f32_e32 v77, 0x3dd53b94, v47
	v_pk_fma_f32 v[140:141], v[16:17], s[60:61], v[74:75] op_sel_hi:[1,0,0]
	v_bitop3_b32 v16, v60, 15, s33 bitop3:0xc8
	v_exp_f32_e32 v175, v32
	v_exp_f32_e32 v217, v33
	v_exp_f32_e32 v149, v34
	v_exp_f32_e32 v216, v35
	v_exp_f32_e32 v150, v36
	v_exp_f32_e32 v174, v37
	v_exp_f32_e32 v151, v38
	v_exp_f32_e32 v173, v39
	v_exp_f32_e32 v154, v40
	v_exp_f32_e32 v172, v41
	v_exp_f32_e32 v153, v42
	v_exp_f32_e32 v155, v43
	v_exp_f32_e32 v145, v44
	v_exp_f32_e32 v147, v45
	v_exp_f32_e32 v144, v46
	v_exp_f32_e32 v146, v77
	v_lshlrev_b32_e32 v16, 4, v16
	v_writelane_b32 v254, s16, 62
	v_mov_b64_e32 v[14:15], s[82:83]
	s_waitcnt vmcnt(0)
	s_addk_i32 s16, 0x4000
	v_or3_b32 v158, v158, s15, v16
	v_bitop3_b32 v16, v60, 7, s33 bitop3:0xc8
	v_mov_b64_e32 v[2:3], s[70:71]
	v_mov_b64_e32 v[4:5], s[72:73]
	v_mov_b64_e32 v[6:7], s[74:75]
	v_mov_b64_e32 v[8:9], s[76:77]
	v_mov_b64_e32 v[10:11], s[78:79]
	v_mov_b64_e32 v[12:13], s[80:81]
	v_pk_fma_f32 v[134:135], v[30:31], s[60:61], v[74:75] op_sel_hi:[1,0,0]
	v_pk_fma_f32 v[136:137], v[28:29], s[60:61], v[74:75] op_sel_hi:[1,0,0]
	v_pk_fma_f32 v[142:143], v[26:27], s[60:61], v[74:75] op_sel_hi:[1,0,0]
	v_pk_fma_f32 v[128:129], v[24:25], s[60:61], v[74:75] op_sel_hi:[1,0,0]
	v_pk_fma_f32 v[130:131], v[22:23], s[60:61], v[74:75] op_sel_hi:[1,0,0]
	v_pk_fma_f32 v[132:133], v[20:21], s[60:61], v[74:75] op_sel_hi:[1,0,0]
	v_pk_fma_f32 v[138:139], v[18:19], s[60:61], v[74:75] op_sel_hi:[1,0,0]
	s_waitcnt vmcnt(4)
	ds_write_b128 v185, v[48:51] offset:16384
	s_waitcnt vmcnt(3)
	ds_write_b128 v186, v[62:65] offset:16384
	s_waitcnt vmcnt(2)
	ds_write_b128 v187, v[66:69] offset:49152
	s_waitcnt vmcnt(1)
	ds_write_b128 v188, v[70:73] offset:49152
	s_waitcnt vmcnt(0)
	ds_write_b128 v208, v[56:59]
	v_add_u32_e32 v180, s16, v61
	v_lshl_or_b32 v170, v16, 4, v170
	v_mov_b64_e32 v[62:63], v[14:15]
	v_mov_b64_e32 v[46:47], v[14:15]
	v_mov_b64_e32 v[30:31], v[14:15]
	v_writelane_b32 v254, s17, 63
	v_cmp_gt_u32_e64 s[4:5], 32, v76
	v_mov_b64_e32 v[60:61], v[12:13]
	v_mov_b64_e32 v[58:59], v[10:11]
	v_mov_b64_e32 v[56:57], v[8:9]
	v_mov_b64_e32 v[54:55], v[6:7]
	v_mov_b64_e32 v[52:53], v[4:5]
	v_mov_b64_e32 v[50:51], v[2:3]
	v_mov_b64_e32 v[48:49], v[0:1]
	v_mov_b64_e32 v[44:45], v[12:13]
	v_mov_b64_e32 v[42:43], v[10:11]
	v_mov_b64_e32 v[40:41], v[8:9]
	v_mov_b64_e32 v[38:39], v[6:7]
	v_mov_b64_e32 v[36:37], v[4:5]
	v_mov_b64_e32 v[34:35], v[2:3]
	v_mov_b64_e32 v[32:33], v[0:1]
	v_mov_b64_e32 v[28:29], v[12:13]
	v_mov_b64_e32 v[26:27], v[10:11]
	v_mov_b64_e32 v[24:25], v[8:9]
	v_mov_b64_e32 v[22:23], v[6:7]
	v_mov_b64_e32 v[20:21], v[4:5]
	v_mov_b64_e32 v[18:19], v[2:3]
	v_mov_b64_e32 v[16:17], v[0:1]
	s_waitcnt lgkmcnt(0)
	s_barrier

.LBB0_870:
	s_or_b64 exec, exec, s[12:13]
	v_cvt_f32_u32_e32 v128, v202
	v_cvt_f32_i32_e32 v141, v203
	v_cvt_f32_u32_e32 v129, v200
	v_cvt_f32_i32_e32 v130, v201
	s_waitcnt vmcnt(12)
	v_lshlrev_b32_e32 v142, 16, v222
	v_fmac_f32_e32 v141, 0x2f800000, v128
	v_mul_f32_e32 v128, 0x3a000000, v141
	v_fmac_f32_e32 v130, 0x2f800000, v129
	v_mul_f32_e32 v128, v128, v128
	v_fma_f32 v128, v130, s94, -v128
	v_add_f32_e32 v128, 0x3727c5ac, v128
	v_rsq_f32_e32 v140, v128
	v_add_u32_e32 v128, 0x80, v176
	v_ashrrev_i32_e32 v129, 31, v128
	v_lshlrev_b64 v[130:131], 12, v[128:129]
	v_lshl_add_u64 v[130:131], s[28:29], 0, v[130:131]
	v_lshl_add_u64 v[130:131], v[186:187], 1, v[130:131]
	global_load_dwordx2 v[138:139], v[130:131], off
	global_load_dwordx2 v[136:137], v[130:131], off offset:32
	global_load_dwordx2 v[134:135], v[130:131], off offset:256
	global_load_dwordx2 v[132:133], v[130:131], off offset:288
	v_and_b32_e32 v143, 0xffff0000, v222
	v_lshlrev_b32_e32 v154, 16, v223
	v_and_b32_e32 v155, 0xffff0000, v223
	v_fmac_f32_e32 v143, 0xba000000, v141
	v_fmac_f32_e32 v142, 0xba000000, v141
	v_fmac_f32_e32 v155, 0xba000000, v141
	v_fmac_f32_e32 v154, 0xba000000, v141
	v_pk_mul_f32 v[154:155], v[140:141], v[154:155] op_sel_hi:[0,1]
	v_pk_mul_f32 v[142:143], v[140:141], v[142:143] op_sel_hi:[0,1]
	v_pk_fma_f32 v[142:143], v[72:73], v[142:143], v[76:77]
	v_pk_fma_f32 v[154:155], v[74:75], v[154:155], v[78:79]
	v_pk_fma_f32 v[124:125], v[142:143], s[62:63], v[124:125] op_sel_hi:[1,0,1]
	v_pk_fma_f32 v[126:127], v[154:155], s[62:63], v[126:127] op_sel_hi:[1,0,1]
	v_cvt_pk_bf16_f32 v142, v124, v125
	v_add_f32_e32 v129, v124, v125
	v_cvt_pk_bf16_f32 v143, v126, v127
	global_store_dwordx2 v[204:205], v[142:143], off
	v_add_f32_e32 v142, v126, v127
	v_pk_mul_f32 v[126:127], v[126:127], v[126:127]
	v_pk_mul_f32 v[124:125], v[124:125], v[124:125]
	v_add_f32_e32 v129, v129, v142
	v_pk_mov_b32 v[142:143], v[124:125], v[126:127] op_sel:[1,0]
	v_mov_b32_e32 v125, v127
	v_pk_add_f32 v[124:125], v[142:143], v[124:125]
	v_lshlrev_b32_e32 v126, 16, v214
	v_and_b32_e32 v127, 0xffff0000, v214
	v_lshlrev_b32_e32 v142, 16, v215
	v_and_b32_e32 v143, 0xffff0000, v215
	v_fmac_f32_e32 v127, 0xba000000, v141
	v_fmac_f32_e32 v126, 0xba000000, v141
	v_fmac_f32_e32 v143, 0xba000000, v141
	v_fmac_f32_e32 v142, 0xba000000, v141
	v_pk_mul_f32 v[142:143], v[140:141], v[142:143] op_sel_hi:[0,1]
	v_pk_mul_f32 v[126:127], v[140:141], v[126:127] op_sel_hi:[0,1]
	v_pk_fma_f32 v[126:127], v[64:65], v[126:127], v[68:69]
	v_pk_fma_f32 v[142:143], v[66:67], v[142:143], v[70:71]
	v_pk_fma_f32 v[120:121], v[126:127], s[62:63], v[120:121] op_sel_hi:[1,0,1]
	v_pk_fma_f32 v[122:123], v[142:143], s[62:63], v[122:123] op_sel_hi:[1,0,1]
	v_cvt_pk_bf16_f32 v126, v120, v121
	v_add_f32_e32 v129, 0, v129
	v_cvt_pk_bf16_f32 v127, v122, v123
	global_store_dwordx2 v[204:205], v[126:127], off offset:32
	v_add_f32_e32 v126, v120, v121
	v_add_f32_e32 v127, v122, v123
	v_add_f32_e32 v126, v126, v127
	v_pk_mul_f32 v[122:123], v[122:123], v[122:123]
	v_pk_mul_f32 v[120:121], v[120:121], v[120:121]
	v_add_f32_e32 v129, v129, v126
	v_pk_mov_b32 v[126:127], v[120:121], v[122:123] op_sel:[1,0]
	v_mov_b32_e32 v121, v123
	v_pk_add_f32 v[120:121], v[126:127], v[120:121]
	v_lshlrev_b32_e32 v122, 16, v210
	v_and_b32_e32 v123, 0xffff0000, v210
	v_lshlrev_b32_e32 v126, 16, v211
	v_and_b32_e32 v127, 0xffff0000, v211
	v_fmac_f32_e32 v123, 0xba000000, v141
	v_fmac_f32_e32 v122, 0xba000000, v141
	v_fmac_f32_e32 v127, 0xba000000, v141
	v_fmac_f32_e32 v126, 0xba000000, v141
	v_pk_mul_f32 v[126:127], v[140:141], v[126:127] op_sel_hi:[0,1]
	v_pk_mul_f32 v[122:123], v[140:141], v[122:123] op_sel_hi:[0,1]
	v_pk_fma_f32 v[122:123], v[56:57], v[122:123], v[60:61]
	v_pk_fma_f32 v[126:127], v[58:59], v[126:127], v[62:63]
	v_pk_fma_f32 v[116:117], v[122:123], s[62:63], v[116:117] op_sel_hi:[1,0,1]
	v_pk_fma_f32 v[118:119], v[126:127], s[62:63], v[118:119] op_sel_hi:[1,0,1]
	v_cvt_pk_bf16_f32 v122, v116, v117
	v_lshlrev_b32_e32 v126, 16, v209
	v_cvt_pk_bf16_f32 v123, v118, v119
	global_store_dwordx2 v[204:205], v[122:123], off offset:256
	v_add_f32_e32 v122, v116, v117
	v_add_f32_e32 v123, v118, v119
	v_add_f32_e32 v122, v122, v123
	v_add_f32_e32 v129, v129, v122
	v_lshlrev_b32_e32 v122, 16, v208
	v_and_b32_e32 v123, 0xffff0000, v208
	v_and_b32_e32 v127, 0xffff0000, v209
	v_fmac_f32_e32 v123, 0xba000000, v141
	v_fmac_f32_e32 v122, 0xba000000, v141
	v_fmac_f32_e32 v127, 0xba000000, v141
	v_fmac_f32_e32 v126, 0xba000000, v141
	v_pk_mul_f32 v[126:127], v[140:141], v[126:127] op_sel_hi:[0,1]
	v_pk_mul_f32 v[122:123], v[140:141], v[122:123] op_sel_hi:[0,1]
	v_pk_fma_f32 v[122:123], v[48:49], v[122:123], v[52:53]
	v_pk_fma_f32 v[126:127], v[50:51], v[126:127], v[54:55]
	v_pk_fma_f32 v[112:113], v[122:123], s[62:63], v[112:113] op_sel_hi:[1,0,1]
	v_pk_fma_f32 v[114:115], v[126:127], s[62:63], v[114:115] op_sel_hi:[1,0,1]
	v_cvt_pk_bf16_f32 v122, v112, v113
	v_mul_f32_e32 v126, v113, v113
	v_cvt_pk_bf16_f32 v123, v114, v115
	global_store_dwordx2 v[204:205], v[122:123], off offset:288
	v_add_f32_e32 v122, v112, v113
	v_add_f32_e32 v123, v114, v115
	v_add_f32_e32 v122, v122, v123
	v_add_f32_e32 v122, v129, v122
	v_mul_f32_e32 v123, v112, v112
	v_mul_f32_e32 v127, v114, v114
	v_mul_f32_e32 v129, v115, v115
	v_pk_add_f32 v[112:113], v[124:125], v[124:125] op_sel:[0,1] op_sel_hi:[1,0]
	v_pk_add_f32 v[114:115], v[120:121], v[120:121] op_sel:[0,1] op_sel_hi:[1,0]
	v_mov_b32_e32 v113, v123
	v_mov_b32_e32 v115, v126
	v_pk_add_f32 v[112:113], v[112:113], v[114:115]
	v_mul_f32_e32 v114, v117, v117
	v_pk_fma_f32 v[114:115], v[116:117], v[116:117], v[114:115] op_sel_hi:[1,1,0]
	v_mul_f32_e32 v116, v119, v119
	v_pk_fma_f32 v[116:117], v[118:119], v[118:119], v[116:117] op_sel_hi:[1,1,0]
	v_mov_b32_e32 v115, v127
	v_mov_b32_e32 v117, v129
	v_pk_add_f32 v[114:115], v[114:115], v[116:117]
	v_cmp_lt_i32_e64 s[8:9], 0, v247
	v_pk_add_f32 v[112:113], v[112:113], v[114:115]
	s_mov_b64 s[0:1], 0
	v_pk_add_f32 v[112:113], v[112:113], v[112:113] op_sel:[0,1] op_sel_hi:[1,0]
	s_nop 0
	v_mov_b32_e32 v113, v122
	s_nop 1
	v_permlane16_swap_b32_e32 v122, v113
	v_add_f32_e32 v116, v122, v113
	v_mov_b32_e32 v113, v112
	s_nop 1
	v_permlane16_swap_b32_e32 v112, v113
	v_add_f32_e32 v114, v112, v113
	v_mov_b32_e32 v117, v116
	v_mov_b32_e32 v115, v114
	s_nop 0
	v_permlane32_swap_b32_e32 v116, v117
	v_permlane32_swap_b32_e32 v114, v115
	s_and_saveexec_b64 s[12:13], s[8:9]
	s_xor_b64 s[8:9], exec, s[12:13]
	s_cbranch_execnz .LBB0_895
	s_or_saveexec_b64 s[8:9], s[8:9]
	v_mov_b64_e32 v[112:113], 0xc0000
	s_xor_b64 exec, exec, s[8:9]
	s_cbranch_execnz .LBB0_896

.LBB0_874:
	s_or_b64 exec, exec, s[12:13]
	s_waitcnt vmcnt(12)
	v_cvt_f32_u32_e32 v112, v198
	v_cvt_f32_i32_e32 v123, v199
	v_cvt_f32_u32_e32 v113, v196
	v_cvt_f32_i32_e32 v114, v197
	v_lshlrev_b32_e32 v124, 16, v152
	v_fmac_f32_e32 v123, 0x2f800000, v112
	v_mul_f32_e32 v112, 0x3a000000, v123
	v_fmac_f32_e32 v114, 0x2f800000, v113
	v_mul_f32_e32 v112, v112, v112
	v_fma_f32 v112, v114, s94, -v112
	v_add_f32_e32 v112, 0x3727c5ac, v112
	v_rsq_f32_e32 v122, v112
	v_or_b32_e32 v112, 16, v128
	v_ashrrev_i32_e32 v113, 31, v112
	v_lshlrev_b64 v[112:113], 12, v[112:113]
	v_lshl_add_u64 v[112:113], s[28:29], 0, v[112:113]
	v_lshl_add_u64 v[112:113], v[186:187], 1, v[112:113]
	global_load_dwordx2 v[120:121], v[112:113], off
	global_load_dwordx2 v[118:119], v[112:113], off offset:32
	global_load_dwordx2 v[116:117], v[112:113], off offset:256
	global_load_dwordx2 v[114:115], v[112:113], off offset:288
	v_and_b32_e32 v125, 0xffff0000, v152
	v_lshlrev_b32_e32 v126, 16, v153
	v_and_b32_e32 v127, 0xffff0000, v153
	v_fmac_f32_e32 v125, 0xba000000, v123
	v_fmac_f32_e32 v124, 0xba000000, v123
	v_fmac_f32_e32 v127, 0xba000000, v123
	v_fmac_f32_e32 v126, 0xba000000, v123
	v_pk_mul_f32 v[126:127], v[122:123], v[126:127] op_sel_hi:[0,1]
	v_pk_mul_f32 v[124:125], v[122:123], v[124:125] op_sel_hi:[0,1]
	v_pk_fma_f32 v[124:125], v[72:73], v[124:125], v[76:77]
	v_pk_fma_f32 v[126:127], v[74:75], v[126:127], v[78:79]
	v_pk_fma_f32 v[108:109], v[124:125], s[62:63], v[108:109] op_sel_hi:[1,0,1]
	v_pk_fma_f32 v[110:111], v[126:127], s[62:63], v[110:111] op_sel_hi:[1,0,1]
	v_cvt_pk_bf16_f32 v124, v108, v109
	v_cmp_lt_i32_e64 s[8:9], 0, v247
	v_cvt_pk_bf16_f32 v125, v110, v111
	global_store_dwordx2 v[144:145], v[124:125], off
	v_add_f32_e32 v124, v108, v109
	v_add_f32_e32 v125, v110, v111
	v_add_f32_e32 v124, v124, v125
	v_pk_mul_f32 v[110:111], v[110:111], v[110:111]
	v_pk_mul_f32 v[108:109], v[108:109], v[108:109]
	v_add_f32_e32 v126, 0, v124
	v_pk_mov_b32 v[124:125], v[108:109], v[110:111] op_sel:[1,0]
	v_mov_b32_e32 v109, v111
	v_pk_add_f32 v[108:109], v[124:125], v[108:109]
	v_lshlrev_b32_e32 v110, 16, v150
	v_and_b32_e32 v111, 0xffff0000, v150
	v_lshlrev_b32_e32 v124, 16, v151
	v_and_b32_e32 v125, 0xffff0000, v151
	v_fmac_f32_e32 v111, 0xba000000, v123
	v_fmac_f32_e32 v110, 0xba000000, v123
	v_fmac_f32_e32 v125, 0xba000000, v123
	v_fmac_f32_e32 v124, 0xba000000, v123
	v_pk_mul_f32 v[124:125], v[122:123], v[124:125] op_sel_hi:[0,1]
	v_pk_mul_f32 v[110:111], v[122:123], v[110:111] op_sel_hi:[0,1]
	v_pk_fma_f32 v[110:111], v[64:65], v[110:111], v[68:69]
	v_pk_fma_f32 v[124:125], v[66:67], v[124:125], v[70:71]
	v_pk_fma_f32 v[104:105], v[110:111], s[62:63], v[104:105] op_sel_hi:[1,0,1]
	v_pk_fma_f32 v[106:107], v[124:125], s[62:63], v[106:107] op_sel_hi:[1,0,1]
	v_cvt_pk_bf16_f32 v110, v104, v105
	s_mov_b64 s[0:1], 0
	v_cvt_pk_bf16_f32 v111, v106, v107
	global_store_dwordx2 v[144:145], v[110:111], off offset:32
	v_add_f32_e32 v110, v104, v105
	v_add_f32_e32 v111, v106, v107
	v_add_f32_e32 v110, v110, v111
	v_pk_mul_f32 v[106:107], v[106:107], v[106:107]
	v_pk_mul_f32 v[104:105], v[104:105], v[104:105]
	v_add_f32_e32 v124, v126, v110
	v_pk_mov_b32 v[110:111], v[104:105], v[106:107] op_sel:[1,0]
	v_mov_b32_e32 v105, v107
	v_pk_add_f32 v[104:105], v[110:111], v[104:105]
	v_lshlrev_b32_e32 v106, 16, v148
	v_and_b32_e32 v107, 0xffff0000, v148
	v_lshlrev_b32_e32 v110, 16, v149
	v_and_b32_e32 v111, 0xffff0000, v149
	v_fmac_f32_e32 v107, 0xba000000, v123
	v_fmac_f32_e32 v106, 0xba000000, v123
	v_fmac_f32_e32 v111, 0xba000000, v123
	v_fmac_f32_e32 v110, 0xba000000, v123
	v_pk_mul_f32 v[110:111], v[122:123], v[110:111] op_sel_hi:[0,1]
	v_pk_mul_f32 v[106:107], v[122:123], v[106:107] op_sel_hi:[0,1]
	v_pk_fma_f32 v[106:107], v[56:57], v[106:107], v[60:61]
	v_pk_fma_f32 v[110:111], v[58:59], v[110:111], v[62:63]
	v_pk_fma_f32 v[100:101], v[106:107], s[62:63], v[100:101] op_sel_hi:[1,0,1]
	v_pk_fma_f32 v[102:103], v[110:111], s[62:63], v[102:103] op_sel_hi:[1,0,1]
	v_cvt_pk_bf16_f32 v106, v100, v101
	v_lshlrev_b32_e32 v110, 16, v147
	v_cvt_pk_bf16_f32 v107, v102, v103
	global_store_dwordx2 v[144:145], v[106:107], off offset:256
	v_add_f32_e32 v106, v100, v101
	v_add_f32_e32 v107, v102, v103
	v_add_f32_e32 v106, v106, v107
	v_add_f32_e32 v124, v124, v106
	v_lshlrev_b32_e32 v106, 16, v146
	v_and_b32_e32 v107, 0xffff0000, v146
	v_and_b32_e32 v111, 0xffff0000, v147
	v_fmac_f32_e32 v107, 0xba000000, v123
	v_fmac_f32_e32 v106, 0xba000000, v123
	v_fmac_f32_e32 v111, 0xba000000, v123
	v_fmac_f32_e32 v110, 0xba000000, v123
	v_pk_mul_f32 v[110:111], v[122:123], v[110:111] op_sel_hi:[0,1]
	v_pk_mul_f32 v[106:107], v[122:123], v[106:107] op_sel_hi:[0,1]
	v_pk_fma_f32 v[106:107], v[48:49], v[106:107], v[52:53]
	v_pk_fma_f32 v[110:111], v[50:51], v[110:111], v[54:55]
	v_pk_fma_f32 v[96:97], v[106:107], s[62:63], v[96:97] op_sel_hi:[1,0,1]
	v_pk_fma_f32 v[98:99], v[110:111], s[62:63], v[98:99] op_sel_hi:[1,0,1]
	v_cvt_pk_bf16_f32 v106, v96, v97
	v_mul_f32_e32 v110, v97, v97
	v_cvt_pk_bf16_f32 v107, v98, v99
	global_store_dwordx2 v[144:145], v[106:107], off offset:288
	v_add_f32_e32 v106, v96, v97
	v_add_f32_e32 v107, v98, v99
	v_add_f32_e32 v106, v106, v107
	v_mul_f32_e32 v107, v96, v96
	v_mul_f32_e32 v111, v98, v98
	v_mul_f32_e32 v122, v99, v99
	v_pk_add_f32 v[96:97], v[108:109], v[108:109] op_sel:[0,1] op_sel_hi:[1,0]
	v_pk_add_f32 v[98:99], v[104:105], v[104:105] op_sel:[0,1] op_sel_hi:[1,0]
	v_mov_b32_e32 v97, v107
	v_mov_b32_e32 v99, v110
	v_pk_add_f32 v[96:97], v[96:97], v[98:99]
	v_mul_f32_e32 v98, v101, v101
	v_pk_fma_f32 v[98:99], v[100:101], v[100:101], v[98:99] op_sel_hi:[1,1,0]
	v_mul_f32_e32 v100, v103, v103
	v_pk_fma_f32 v[100:101], v[102:103], v[102:103], v[100:101] op_sel_hi:[1,1,0]
	v_mov_b32_e32 v99, v111
	v_mov_b32_e32 v101, v122
	v_pk_add_f32 v[98:99], v[98:99], v[100:101]
	v_add_f32_e32 v106, v124, v106
	v_pk_add_f32 v[96:97], v[96:97], v[98:99]
	s_nop 0
	v_pk_add_f32 v[96:97], v[96:97], v[96:97] op_sel:[0,1] op_sel_hi:[1,0]
	s_nop 0
	v_mov_b32_e32 v97, v106
	s_nop 1
	v_permlane16_swap_b32_e32 v106, v97
	v_add_f32_e32 v100, v106, v97
	v_mov_b32_e32 v97, v96
	s_nop 1
	v_permlane16_swap_b32_e32 v96, v97
	v_add_f32_e32 v98, v96, v97
	v_mov_b32_e32 v101, v100
	v_mov_b32_e32 v99, v98
	s_nop 0
	v_permlane32_swap_b32_e32 v100, v101
	v_permlane32_swap_b32_e32 v98, v99
	s_and_saveexec_b64 s[12:13], s[8:9]
	s_xor_b64 s[8:9], exec, s[12:13]
	s_cbranch_execnz .LBB0_897
	s_or_saveexec_b64 s[8:9], s[8:9]
	v_mov_b64_e32 v[96:97], 0xc0000
	s_xor_b64 exec, exec, s[8:9]
	s_cbranch_execnz .LBB0_898

.LBB0_878:
	s_or_b64 exec, exec, s[12:13]
	v_cvt_f32_u32_e32 v96, v194
	v_cvt_f32_i32_e32 v107, v195
	v_cvt_f32_u32_e32 v97, v192
	v_cvt_f32_i32_e32 v98, v193
	s_waitcnt vmcnt(12)
	v_lshlrev_b32_e32 v108, 16, v138
	v_fmac_f32_e32 v107, 0x2f800000, v96
	v_mul_f32_e32 v96, 0x3a000000, v107
	v_fmac_f32_e32 v98, 0x2f800000, v97
	v_mul_f32_e32 v96, v96, v96
	v_fma_f32 v96, v98, s94, -v96
	v_add_f32_e32 v96, 0x3727c5ac, v96
	v_rsq_f32_e32 v106, v96
	v_or_b32_e32 v96, 32, v128
	v_ashrrev_i32_e32 v97, 31, v96
	v_lshlrev_b64 v[96:97], 12, v[96:97]
	v_lshl_add_u64 v[96:97], s[28:29], 0, v[96:97]
	v_lshl_add_u64 v[96:97], v[186:187], 1, v[96:97]
	global_load_dwordx2 v[104:105], v[96:97], off
	global_load_dwordx2 v[102:103], v[96:97], off offset:32
	global_load_dwordx2 v[100:101], v[96:97], off offset:256
	global_load_dwordx2 v[98:99], v[96:97], off offset:288
	v_and_b32_e32 v109, 0xffff0000, v138
	v_lshlrev_b32_e32 v110, 16, v139
	v_and_b32_e32 v111, 0xffff0000, v139
	v_fmac_f32_e32 v109, 0xba000000, v107
	v_fmac_f32_e32 v108, 0xba000000, v107
	v_fmac_f32_e32 v111, 0xba000000, v107
	v_fmac_f32_e32 v110, 0xba000000, v107
	v_pk_mul_f32 v[110:111], v[106:107], v[110:111] op_sel_hi:[0,1]
	v_pk_mul_f32 v[108:109], v[106:107], v[108:109] op_sel_hi:[0,1]
	v_pk_fma_f32 v[108:109], v[72:73], v[108:109], v[76:77]
	v_pk_fma_f32 v[110:111], v[74:75], v[110:111], v[78:79]
	v_pk_fma_f32 v[92:93], v[108:109], s[62:63], v[92:93] op_sel_hi:[1,0,1]
	v_pk_fma_f32 v[94:95], v[110:111], s[62:63], v[94:95] op_sel_hi:[1,0,1]
	v_cvt_pk_bf16_f32 v108, v92, v93
	v_cmp_lt_i32_e64 s[8:9], 0, v247
	v_cvt_pk_bf16_f32 v109, v94, v95
	global_store_dwordx2 v[130:131], v[108:109], off
	v_add_f32_e32 v108, v92, v93
	v_add_f32_e32 v109, v94, v95
	v_add_f32_e32 v108, v108, v109
	v_pk_mul_f32 v[94:95], v[94:95], v[94:95]
	v_pk_mul_f32 v[92:93], v[92:93], v[92:93]
	v_add_f32_e32 v110, 0, v108
	v_pk_mov_b32 v[108:109], v[92:93], v[94:95] op_sel:[1,0]
	v_mov_b32_e32 v93, v95
	v_pk_add_f32 v[92:93], v[108:109], v[92:93]
	v_lshlrev_b32_e32 v94, 16, v136
	v_and_b32_e32 v95, 0xffff0000, v136
	v_lshlrev_b32_e32 v108, 16, v137
	v_and_b32_e32 v109, 0xffff0000, v137
	v_fmac_f32_e32 v95, 0xba000000, v107
	v_fmac_f32_e32 v94, 0xba000000, v107
	v_fmac_f32_e32 v109, 0xba000000, v107
	v_fmac_f32_e32 v108, 0xba000000, v107
	v_pk_mul_f32 v[108:109], v[106:107], v[108:109] op_sel_hi:[0,1]
	v_pk_mul_f32 v[94:95], v[106:107], v[94:95] op_sel_hi:[0,1]
	v_pk_fma_f32 v[94:95], v[64:65], v[94:95], v[68:69]
	v_pk_fma_f32 v[108:109], v[66:67], v[108:109], v[70:71]
	v_pk_fma_f32 v[88:89], v[94:95], s[62:63], v[88:89] op_sel_hi:[1,0,1]
	v_pk_fma_f32 v[90:91], v[108:109], s[62:63], v[90:91] op_sel_hi:[1,0,1]
	v_cvt_pk_bf16_f32 v94, v88, v89
	s_mov_b64 s[0:1], 0
	v_cvt_pk_bf16_f32 v95, v90, v91
	global_store_dwordx2 v[130:131], v[94:95], off offset:32
	v_add_f32_e32 v94, v88, v89
	v_add_f32_e32 v95, v90, v91
	v_add_f32_e32 v94, v94, v95
	v_pk_mul_f32 v[90:91], v[90:91], v[90:91]
	v_pk_mul_f32 v[88:89], v[88:89], v[88:89]
	v_add_f32_e32 v108, v110, v94
	v_pk_mov_b32 v[94:95], v[88:89], v[90:91] op_sel:[1,0]
	v_mov_b32_e32 v89, v91
	v_pk_add_f32 v[88:89], v[94:95], v[88:89]
	v_lshlrev_b32_e32 v90, 16, v134
	v_and_b32_e32 v91, 0xffff0000, v134
	v_lshlrev_b32_e32 v94, 16, v135
	v_and_b32_e32 v95, 0xffff0000, v135
	v_fmac_f32_e32 v91, 0xba000000, v107
	v_fmac_f32_e32 v90, 0xba000000, v107
	v_fmac_f32_e32 v95, 0xba000000, v107
	v_fmac_f32_e32 v94, 0xba000000, v107
	v_pk_mul_f32 v[94:95], v[106:107], v[94:95] op_sel_hi:[0,1]
	v_pk_mul_f32 v[90:91], v[106:107], v[90:91] op_sel_hi:[0,1]
	v_pk_fma_f32 v[90:91], v[56:57], v[90:91], v[60:61]
	v_pk_fma_f32 v[94:95], v[58:59], v[94:95], v[62:63]
	v_pk_fma_f32 v[84:85], v[90:91], s[62:63], v[84:85] op_sel_hi:[1,0,1]
	v_pk_fma_f32 v[86:87], v[94:95], s[62:63], v[86:87] op_sel_hi:[1,0,1]
	v_cvt_pk_bf16_f32 v90, v84, v85
	v_lshlrev_b32_e32 v94, 16, v133
	v_cvt_pk_bf16_f32 v91, v86, v87
	global_store_dwordx2 v[130:131], v[90:91], off offset:256
	v_add_f32_e32 v90, v84, v85
	v_add_f32_e32 v91, v86, v87
	v_add_f32_e32 v90, v90, v91
	v_add_f32_e32 v108, v108, v90
	v_lshlrev_b32_e32 v90, 16, v132
	v_and_b32_e32 v91, 0xffff0000, v132
	v_and_b32_e32 v95, 0xffff0000, v133
	v_fmac_f32_e32 v91, 0xba000000, v107
	v_fmac_f32_e32 v90, 0xba000000, v107
	v_fmac_f32_e32 v95, 0xba000000, v107
	v_fmac_f32_e32 v94, 0xba000000, v107
	v_pk_mul_f32 v[94:95], v[106:107], v[94:95] op_sel_hi:[0,1]
	v_pk_mul_f32 v[90:91], v[106:107], v[90:91] op_sel_hi:[0,1]
	v_pk_fma_f32 v[90:91], v[48:49], v[90:91], v[52:53]
	v_pk_fma_f32 v[94:95], v[50:51], v[94:95], v[54:55]
	v_pk_fma_f32 v[80:81], v[90:91], s[62:63], v[80:81] op_sel_hi:[1,0,1]
	v_pk_fma_f32 v[82:83], v[94:95], s[62:63], v[82:83] op_sel_hi:[1,0,1]
	v_cvt_pk_bf16_f32 v90, v80, v81
	v_mul_f32_e32 v94, v81, v81
	v_cvt_pk_bf16_f32 v91, v82, v83
	global_store_dwordx2 v[130:131], v[90:91], off offset:288
	v_add_f32_e32 v90, v80, v81
	v_add_f32_e32 v91, v82, v83
	v_add_f32_e32 v90, v90, v91
	v_mul_f32_e32 v91, v80, v80
	v_mul_f32_e32 v95, v82, v82
	v_mul_f32_e32 v106, v83, v83
	v_pk_add_f32 v[80:81], v[92:93], v[92:93] op_sel:[0,1] op_sel_hi:[1,0]
	v_pk_add_f32 v[82:83], v[88:89], v[88:89] op_sel:[0,1] op_sel_hi:[1,0]
	v_mov_b32_e32 v81, v91
	v_mov_b32_e32 v83, v94
	v_pk_add_f32 v[80:81], v[80:81], v[82:83]
	v_mul_f32_e32 v82, v85, v85
	v_pk_fma_f32 v[82:83], v[84:85], v[84:85], v[82:83] op_sel_hi:[1,1,0]
	v_mul_f32_e32 v84, v87, v87
	v_pk_fma_f32 v[84:85], v[86:87], v[86:87], v[84:85] op_sel_hi:[1,1,0]
	v_mov_b32_e32 v83, v95
	v_mov_b32_e32 v85, v106
	v_pk_add_f32 v[82:83], v[82:83], v[84:85]
	v_add_f32_e32 v90, v108, v90
	v_pk_add_f32 v[80:81], v[80:81], v[82:83]
	s_nop 0
	v_pk_add_f32 v[80:81], v[80:81], v[80:81] op_sel:[0,1] op_sel_hi:[1,0]
	s_nop 0
	v_mov_b32_e32 v81, v90
	s_nop 1
	v_permlane16_swap_b32_e32 v90, v81
	v_add_f32_e32 v84, v90, v81
	v_mov_b32_e32 v81, v80
	s_nop 1
	v_permlane16_swap_b32_e32 v80, v81
	v_add_f32_e32 v82, v80, v81
	v_mov_b32_e32 v85, v84
	v_mov_b32_e32 v83, v82
	s_nop 0
	v_permlane32_swap_b32_e32 v84, v85
	v_permlane32_swap_b32_e32 v82, v83
	s_and_saveexec_b64 s[12:13], s[8:9]
	s_xor_b64 s[8:9], exec, s[12:13]
	s_cbranch_execnz .LBB0_899
	s_or_saveexec_b64 s[8:9], s[8:9]
	v_mov_b64_e32 v[80:81], 0xc0000
	s_xor_b64 exec, exec, s[8:9]
	s_cbranch_execnz .LBB0_900

.LBB0_882:
	s_or_b64 exec, exec, s[12:13]
	s_waitcnt vmcnt(12)
	v_cvt_f32_u32_e32 v80, v190
	v_cvt_f32_i32_e32 v91, v191
	v_cvt_f32_u32_e32 v81, v188
	v_cvt_f32_i32_e32 v82, v189
	v_lshlrev_b32_e32 v92, 16, v120
	v_fmac_f32_e32 v91, 0x2f800000, v80
	v_mul_f32_e32 v80, 0x3a000000, v91
	v_fmac_f32_e32 v82, 0x2f800000, v81
	v_mul_f32_e32 v80, v80, v80
	v_fma_f32 v80, v82, s94, -v80
	v_add_f32_e32 v80, 0x3727c5ac, v80
	v_rsq_f32_e32 v90, v80
	v_or_b32_e32 v80, 48, v128
	v_ashrrev_i32_e32 v81, 31, v80
	v_lshlrev_b64 v[80:81], 12, v[80:81]
	v_lshl_add_u64 v[80:81], s[28:29], 0, v[80:81]
	v_lshl_add_u64 v[80:81], v[186:187], 1, v[80:81]
	global_load_dwordx2 v[88:89], v[80:81], off
	global_load_dwordx2 v[86:87], v[80:81], off offset:32
	global_load_dwordx2 v[84:85], v[80:81], off offset:256
	global_load_dwordx2 v[82:83], v[80:81], off offset:288
	v_and_b32_e32 v93, 0xffff0000, v120
	v_lshlrev_b32_e32 v94, 16, v121
	v_and_b32_e32 v95, 0xffff0000, v121
	v_fmac_f32_e32 v93, 0xba000000, v91
	v_fmac_f32_e32 v92, 0xba000000, v91
	v_fmac_f32_e32 v95, 0xba000000, v91
	v_fmac_f32_e32 v94, 0xba000000, v91
	v_pk_mul_f32 v[94:95], v[90:91], v[94:95] op_sel_hi:[0,1]
	v_pk_mul_f32 v[92:93], v[90:91], v[92:93] op_sel_hi:[0,1]
	v_pk_fma_f32 v[92:93], v[72:73], v[92:93], v[76:77]
	v_pk_fma_f32 v[94:95], v[74:75], v[94:95], v[78:79]
	v_pk_fma_f32 v[44:45], v[92:93], s[62:63], v[44:45] op_sel_hi:[1,0,1]
	v_pk_fma_f32 v[46:47], v[94:95], s[62:63], v[46:47] op_sel_hi:[1,0,1]
	v_cvt_pk_bf16_f32 v92, v44, v45
	v_cmp_lt_i32_e64 s[8:9], 0, v247
	v_cvt_pk_bf16_f32 v93, v46, v47
	global_store_dwordx2 v[112:113], v[92:93], off
	v_add_f32_e32 v92, v44, v45
	v_add_f32_e32 v93, v46, v47
	v_add_f32_e32 v92, v92, v93
	v_pk_mul_f32 v[46:47], v[46:47], v[46:47]
	v_pk_mul_f32 v[44:45], v[44:45], v[44:45]
	v_add_f32_e32 v94, 0, v92
	v_pk_mov_b32 v[92:93], v[44:45], v[46:47] op_sel:[1,0]
	v_mov_b32_e32 v45, v47
	v_pk_add_f32 v[44:45], v[92:93], v[44:45]
	v_lshlrev_b32_e32 v46, 16, v118
	v_and_b32_e32 v47, 0xffff0000, v118
	v_lshlrev_b32_e32 v92, 16, v119
	v_and_b32_e32 v93, 0xffff0000, v119
	v_fmac_f32_e32 v47, 0xba000000, v91
	v_fmac_f32_e32 v46, 0xba000000, v91
	v_fmac_f32_e32 v93, 0xba000000, v91
	v_fmac_f32_e32 v92, 0xba000000, v91
	v_pk_mul_f32 v[92:93], v[90:91], v[92:93] op_sel_hi:[0,1]
	v_pk_mul_f32 v[46:47], v[90:91], v[46:47] op_sel_hi:[0,1]
	v_pk_fma_f32 v[46:47], v[64:65], v[46:47], v[68:69]
	v_pk_fma_f32 v[92:93], v[66:67], v[92:93], v[70:71]
	v_pk_fma_f32 v[40:41], v[46:47], s[62:63], v[40:41] op_sel_hi:[1,0,1]
	v_pk_fma_f32 v[42:43], v[92:93], s[62:63], v[42:43] op_sel_hi:[1,0,1]
	v_cvt_pk_bf16_f32 v46, v40, v41
	s_mov_b64 s[0:1], 0
	v_cvt_pk_bf16_f32 v47, v42, v43
	global_store_dwordx2 v[112:113], v[46:47], off offset:32
	v_add_f32_e32 v46, v40, v41
	v_add_f32_e32 v47, v42, v43
	v_add_f32_e32 v46, v46, v47
	v_pk_mul_f32 v[42:43], v[42:43], v[42:43]
	v_pk_mul_f32 v[40:41], v[40:41], v[40:41]
	v_add_f32_e32 v92, v94, v46
	v_pk_mov_b32 v[46:47], v[40:41], v[42:43] op_sel:[1,0]
	v_mov_b32_e32 v41, v43
	v_pk_add_f32 v[40:41], v[46:47], v[40:41]
	v_lshlrev_b32_e32 v42, 16, v116
	v_and_b32_e32 v43, 0xffff0000, v116
	v_lshlrev_b32_e32 v46, 16, v117
	v_and_b32_e32 v47, 0xffff0000, v117
	v_fmac_f32_e32 v43, 0xba000000, v91
	v_fmac_f32_e32 v42, 0xba000000, v91
	v_fmac_f32_e32 v47, 0xba000000, v91
	v_fmac_f32_e32 v46, 0xba000000, v91
	v_pk_mul_f32 v[46:47], v[90:91], v[46:47] op_sel_hi:[0,1]
	v_pk_mul_f32 v[42:43], v[90:91], v[42:43] op_sel_hi:[0,1]
	v_pk_fma_f32 v[42:43], v[56:57], v[42:43], v[60:61]
	v_pk_fma_f32 v[46:47], v[58:59], v[46:47], v[62:63]
	v_pk_fma_f32 v[36:37], v[42:43], s[62:63], v[36:37] op_sel_hi:[1,0,1]
	v_pk_fma_f32 v[38:39], v[46:47], s[62:63], v[38:39] op_sel_hi:[1,0,1]
	v_cvt_pk_bf16_f32 v42, v36, v37
	v_lshlrev_b32_e32 v46, 16, v115
	v_cvt_pk_bf16_f32 v43, v38, v39
	global_store_dwordx2 v[112:113], v[42:43], off offset:256
	v_add_f32_e32 v42, v36, v37
	v_add_f32_e32 v43, v38, v39
	v_add_f32_e32 v42, v42, v43
	v_add_f32_e32 v92, v92, v42
	v_lshlrev_b32_e32 v42, 16, v114
	v_and_b32_e32 v43, 0xffff0000, v114
	v_and_b32_e32 v47, 0xffff0000, v115
	v_fmac_f32_e32 v43, 0xba000000, v91
	v_fmac_f32_e32 v42, 0xba000000, v91
	v_fmac_f32_e32 v47, 0xba000000, v91
	v_fmac_f32_e32 v46, 0xba000000, v91
	v_pk_mul_f32 v[46:47], v[90:91], v[46:47] op_sel_hi:[0,1]
	v_pk_mul_f32 v[42:43], v[90:91], v[42:43] op_sel_hi:[0,1]
	v_pk_fma_f32 v[42:43], v[48:49], v[42:43], v[52:53]
	v_pk_fma_f32 v[46:47], v[50:51], v[46:47], v[54:55]
	v_pk_fma_f32 v[32:33], v[42:43], s[62:63], v[32:33] op_sel_hi:[1,0,1]
	v_pk_fma_f32 v[34:35], v[46:47], s[62:63], v[34:35] op_sel_hi:[1,0,1]
	v_cvt_pk_bf16_f32 v42, v32, v33
	v_mul_f32_e32 v46, v33, v33
	v_cvt_pk_bf16_f32 v43, v34, v35
	global_store_dwordx2 v[112:113], v[42:43], off offset:288
	v_add_f32_e32 v42, v32, v33
	v_add_f32_e32 v43, v34, v35
	v_add_f32_e32 v42, v42, v43
	v_mul_f32_e32 v43, v32, v32
	v_mul_f32_e32 v47, v34, v34
	v_mul_f32_e32 v90, v35, v35
	v_pk_add_f32 v[32:33], v[44:45], v[44:45] op_sel:[0,1] op_sel_hi:[1,0]
	v_pk_add_f32 v[34:35], v[40:41], v[40:41] op_sel:[0,1] op_sel_hi:[1,0]
	v_mov_b32_e32 v33, v43
	v_mov_b32_e32 v35, v46
	v_pk_add_f32 v[32:33], v[32:33], v[34:35]
	v_mul_f32_e32 v34, v37, v37
	v_pk_fma_f32 v[34:35], v[36:37], v[36:37], v[34:35] op_sel_hi:[1,1,0]
	v_mul_f32_e32 v36, v39, v39
	v_pk_fma_f32 v[36:37], v[38:39], v[38:39], v[36:37] op_sel_hi:[1,1,0]
	v_mov_b32_e32 v35, v47
	v_mov_b32_e32 v37, v90
	v_pk_add_f32 v[34:35], v[34:35], v[36:37]
	v_add_f32_e32 v42, v92, v42
	v_pk_add_f32 v[32:33], v[32:33], v[34:35]
	s_nop 0
	v_pk_add_f32 v[32:33], v[32:33], v[32:33] op_sel:[0,1] op_sel_hi:[1,0]
	s_nop 0
	v_mov_b32_e32 v33, v42
	s_nop 1
	v_permlane16_swap_b32_e32 v42, v33
	v_add_f32_e32 v36, v42, v33
	v_mov_b32_e32 v33, v32
	s_nop 1
	v_permlane16_swap_b32_e32 v32, v33
	v_add_f32_e32 v34, v32, v33
	v_mov_b32_e32 v37, v36
	v_mov_b32_e32 v35, v34
	s_nop 0
	v_permlane32_swap_b32_e32 v36, v37
	v_permlane32_swap_b32_e32 v34, v35
	s_and_saveexec_b64 s[12:13], s[8:9]
	s_xor_b64 s[8:9], exec, s[12:13]
	s_cbranch_execnz .LBB0_901
	s_or_saveexec_b64 s[8:9], s[8:9]
	v_mov_b64_e32 v[32:33], 0xc0000
	s_xor_b64 exec, exec, s[8:9]
	s_cbranch_execnz .LBB0_902

.LBB0_886:
	s_or_b64 exec, exec, s[12:13]
	v_cvt_f32_u32_e32 v32, v184
	v_cvt_f32_i32_e32 v33, v185
	v_cvt_f32_u32_e32 v34, v182
	v_cvt_f32_i32_e32 v35, v183
	s_waitcnt vmcnt(12)
	v_lshlrev_b32_e32 v36, 16, v105
	v_fmac_f32_e32 v33, 0x2f800000, v32
	v_mul_f32_e32 v32, 0x3a000000, v33
	v_fmac_f32_e32 v35, 0x2f800000, v34
	v_mul_f32_e32 v32, v32, v32
	v_fma_f32 v32, v35, s94, -v32
	v_add_f32_e32 v32, 0x3727c5ac, v32
	v_rsq_f32_e32 v32, v32
	v_lshlrev_b32_e32 v34, 16, v104
	v_and_b32_e32 v35, 0xffff0000, v104
	v_and_b32_e32 v37, 0xffff0000, v105
	v_fmac_f32_e32 v35, 0xba000000, v33
	v_fmac_f32_e32 v34, 0xba000000, v33
	v_fmac_f32_e32 v37, 0xba000000, v33
	v_fmac_f32_e32 v36, 0xba000000, v33
	v_pk_mul_f32 v[36:37], v[32:33], v[36:37] op_sel_hi:[0,1]
	v_pk_mul_f32 v[34:35], v[32:33], v[34:35] op_sel_hi:[0,1]
	v_pk_fma_f32 v[34:35], v[72:73], v[34:35], v[76:77]
	v_pk_fma_f32 v[36:37], v[74:75], v[36:37], v[78:79]
	v_pk_fma_f32 v[28:29], v[34:35], s[62:63], v[28:29] op_sel_hi:[1,0,1]
	v_pk_fma_f32 v[30:31], v[36:37], s[62:63], v[30:31] op_sel_hi:[1,0,1]
	v_cvt_pk_bf16_f32 v34, v28, v29
	v_cmp_lt_i32_e64 s[8:9], 0, v247
	v_cvt_pk_bf16_f32 v35, v30, v31
	global_store_dwordx2 v[96:97], v[34:35], off
	v_add_f32_e32 v34, v28, v29
	v_add_f32_e32 v35, v30, v31
	v_add_f32_e32 v34, v34, v35
	v_pk_mul_f32 v[30:31], v[30:31], v[30:31]
	v_pk_mul_f32 v[28:29], v[28:29], v[28:29]
	v_add_f32_e32 v36, 0, v34
	v_pk_mov_b32 v[34:35], v[28:29], v[30:31] op_sel:[1,0]
	v_mov_b32_e32 v29, v31
	v_pk_add_f32 v[28:29], v[34:35], v[28:29]
	v_lshlrev_b32_e32 v30, 16, v102
	v_and_b32_e32 v31, 0xffff0000, v102
	v_lshlrev_b32_e32 v34, 16, v103
	v_and_b32_e32 v35, 0xffff0000, v103
	v_fmac_f32_e32 v31, 0xba000000, v33
	v_fmac_f32_e32 v30, 0xba000000, v33
	v_fmac_f32_e32 v35, 0xba000000, v33
	v_fmac_f32_e32 v34, 0xba000000, v33
	v_pk_mul_f32 v[34:35], v[32:33], v[34:35] op_sel_hi:[0,1]
	v_pk_mul_f32 v[30:31], v[32:33], v[30:31] op_sel_hi:[0,1]
	v_pk_fma_f32 v[30:31], v[64:65], v[30:31], v[68:69]
	v_pk_fma_f32 v[34:35], v[66:67], v[34:35], v[70:71]
	v_pk_fma_f32 v[24:25], v[30:31], s[62:63], v[24:25] op_sel_hi:[1,0,1]
	v_pk_fma_f32 v[26:27], v[34:35], s[62:63], v[26:27] op_sel_hi:[1,0,1]
	v_cvt_pk_bf16_f32 v30, v24, v25
	s_mov_b64 s[0:1], 0
	v_cvt_pk_bf16_f32 v31, v26, v27
	global_store_dwordx2 v[96:97], v[30:31], off offset:32
	v_add_f32_e32 v30, v24, v25
	v_add_f32_e32 v31, v26, v27
	v_add_f32_e32 v30, v30, v31
	v_pk_mul_f32 v[26:27], v[26:27], v[26:27]
	v_pk_mul_f32 v[24:25], v[24:25], v[24:25]
	v_add_f32_e32 v34, v36, v30
	v_pk_mov_b32 v[30:31], v[24:25], v[26:27] op_sel:[1,0]
	v_mov_b32_e32 v25, v27
	v_pk_add_f32 v[24:25], v[30:31], v[24:25]
	v_lshlrev_b32_e32 v26, 16, v100
	v_and_b32_e32 v27, 0xffff0000, v100
	v_lshlrev_b32_e32 v30, 16, v101
	v_and_b32_e32 v31, 0xffff0000, v101
	v_fmac_f32_e32 v27, 0xba000000, v33
	v_fmac_f32_e32 v26, 0xba000000, v33
	v_fmac_f32_e32 v31, 0xba000000, v33
	v_fmac_f32_e32 v30, 0xba000000, v33
	v_pk_mul_f32 v[30:31], v[32:33], v[30:31] op_sel_hi:[0,1]
	v_pk_mul_f32 v[26:27], v[32:33], v[26:27] op_sel_hi:[0,1]
	v_pk_fma_f32 v[26:27], v[56:57], v[26:27], v[60:61]
	v_pk_fma_f32 v[30:31], v[58:59], v[30:31], v[62:63]
	v_pk_fma_f32 v[20:21], v[26:27], s[62:63], v[20:21] op_sel_hi:[1,0,1]
	v_pk_fma_f32 v[22:23], v[30:31], s[62:63], v[22:23] op_sel_hi:[1,0,1]
	v_cvt_pk_bf16_f32 v26, v20, v21
	v_lshlrev_b32_e32 v30, 16, v99
	v_cvt_pk_bf16_f32 v27, v22, v23
	global_store_dwordx2 v[96:97], v[26:27], off offset:256
	v_add_f32_e32 v26, v20, v21
	v_add_f32_e32 v27, v22, v23
	v_add_f32_e32 v26, v26, v27
	v_add_f32_e32 v34, v34, v26
	v_lshlrev_b32_e32 v26, 16, v98
	v_and_b32_e32 v27, 0xffff0000, v98
	v_and_b32_e32 v31, 0xffff0000, v99
	v_fmac_f32_e32 v27, 0xba000000, v33
	v_fmac_f32_e32 v26, 0xba000000, v33
	v_fmac_f32_e32 v31, 0xba000000, v33
	v_fmac_f32_e32 v30, 0xba000000, v33
	v_pk_mul_f32 v[30:31], v[32:33], v[30:31] op_sel_hi:[0,1]
	v_pk_mul_f32 v[26:27], v[32:33], v[26:27] op_sel_hi:[0,1]
	v_pk_fma_f32 v[26:27], v[48:49], v[26:27], v[52:53]
	v_pk_fma_f32 v[30:31], v[50:51], v[30:31], v[54:55]
	v_pk_fma_f32 v[16:17], v[26:27], s[62:63], v[16:17] op_sel_hi:[1,0,1]
	v_pk_fma_f32 v[18:19], v[30:31], s[62:63], v[18:19] op_sel_hi:[1,0,1]
	v_cvt_pk_bf16_f32 v26, v16, v17
	v_mul_f32_e32 v30, v17, v17
	v_cvt_pk_bf16_f32 v27, v18, v19
	global_store_dwordx2 v[96:97], v[26:27], off offset:288
	v_add_f32_e32 v26, v16, v17
	v_add_f32_e32 v27, v18, v19
	v_add_f32_e32 v26, v26, v27
	v_mul_f32_e32 v27, v16, v16
	v_mul_f32_e32 v31, v18, v18
	v_mul_f32_e32 v32, v19, v19
	v_pk_add_f32 v[16:17], v[28:29], v[28:29] op_sel:[0,1] op_sel_hi:[1,0]
	v_pk_add_f32 v[18:19], v[24:25], v[24:25] op_sel:[0,1] op_sel_hi:[1,0]
	v_mov_b32_e32 v17, v27
	v_mov_b32_e32 v19, v30
	v_pk_add_f32 v[16:17], v[16:17], v[18:19]
	v_mul_f32_e32 v18, v21, v21
	v_pk_fma_f32 v[18:19], v[20:21], v[20:21], v[18:19] op_sel_hi:[1,1,0]
	v_mul_f32_e32 v20, v23, v23
	v_pk_fma_f32 v[20:21], v[22:23], v[22:23], v[20:21] op_sel_hi:[1,1,0]
	v_mov_b32_e32 v19, v31
	v_mov_b32_e32 v21, v32
	v_pk_add_f32 v[18:19], v[18:19], v[20:21]
	v_add_f32_e32 v26, v34, v26
	v_pk_add_f32 v[16:17], v[16:17], v[18:19]
	s_nop 0
	v_pk_add_f32 v[16:17], v[16:17], v[16:17] op_sel:[0,1] op_sel_hi:[1,0]
	s_nop 0
	v_mov_b32_e32 v17, v26
	s_nop 1
	v_permlane16_swap_b32_e32 v26, v17
	v_add_f32_e32 v20, v26, v17
	v_mov_b32_e32 v17, v16
	s_nop 1
	v_permlane16_swap_b32_e32 v16, v17
	v_add_f32_e32 v18, v16, v17
	v_mov_b32_e32 v21, v20
	v_mov_b32_e32 v19, v18
	s_nop 0
	v_permlane32_swap_b32_e32 v20, v21
	v_permlane32_swap_b32_e32 v18, v19
	s_and_saveexec_b64 s[12:13], s[8:9]
	s_xor_b64 s[8:9], exec, s[12:13]
	s_cbranch_execnz .LBB0_903
	s_or_saveexec_b64 s[8:9], s[8:9]
	v_mov_b64_e32 v[16:17], 0xc0000
	s_xor_b64 exec, exec, s[8:9]
	s_cbranch_execnz .LBB0_904

.LBB0_890:
	s_or_b64 exec, exec, s[12:13]
	s_waitcnt vmcnt(8)
	v_cvt_f32_u32_e32 v16, v180
	v_cvt_f32_i32_e32 v17, v181
	v_cvt_f32_u32_e32 v18, v178
	v_cvt_f32_i32_e32 v19, v179
	v_lshlrev_b32_e32 v20, 16, v89
	v_fmac_f32_e32 v17, 0x2f800000, v16
	v_mul_f32_e32 v16, 0x3a000000, v17
	v_fmac_f32_e32 v19, 0x2f800000, v18
	v_mul_f32_e32 v16, v16, v16
	v_fma_f32 v16, v19, s94, -v16
	v_add_f32_e32 v16, 0x3727c5ac, v16
	v_rsq_f32_e32 v16, v16
	v_lshlrev_b32_e32 v18, 16, v88
	v_and_b32_e32 v19, 0xffff0000, v88
	v_and_b32_e32 v21, 0xffff0000, v89
	v_fmac_f32_e32 v19, 0xba000000, v17
	v_fmac_f32_e32 v18, 0xba000000, v17
	v_fmac_f32_e32 v21, 0xba000000, v17
	v_fmac_f32_e32 v20, 0xba000000, v17
	v_pk_mul_f32 v[20:21], v[16:17], v[20:21] op_sel_hi:[0,1]
	v_pk_mul_f32 v[18:19], v[16:17], v[18:19] op_sel_hi:[0,1]
	v_pk_fma_f32 v[18:19], v[72:73], v[18:19], v[76:77]
	v_pk_fma_f32 v[20:21], v[74:75], v[20:21], v[78:79]
	v_pk_fma_f32 v[12:13], v[18:19], s[62:63], v[12:13] op_sel_hi:[1,0,1]
	v_pk_fma_f32 v[14:15], v[20:21], s[62:63], v[14:15] op_sel_hi:[1,0,1]
	v_cvt_pk_bf16_f32 v18, v12, v13
	v_cmp_lt_i32_e64 s[8:9], 0, v247
	v_cvt_pk_bf16_f32 v19, v14, v15
	global_store_dwordx2 v[80:81], v[18:19], off
	v_add_f32_e32 v18, v12, v13
	v_add_f32_e32 v19, v14, v15
	v_add_f32_e32 v18, v18, v19
	v_pk_mul_f32 v[14:15], v[14:15], v[14:15]
	v_pk_mul_f32 v[12:13], v[12:13], v[12:13]
	v_add_f32_e32 v20, 0, v18
	v_pk_mov_b32 v[18:19], v[12:13], v[14:15] op_sel:[1,0]
	v_mov_b32_e32 v13, v15
	v_pk_add_f32 v[12:13], v[18:19], v[12:13]
	v_lshlrev_b32_e32 v14, 16, v86
	v_and_b32_e32 v15, 0xffff0000, v86
	v_lshlrev_b32_e32 v18, 16, v87
	v_and_b32_e32 v19, 0xffff0000, v87
	v_fmac_f32_e32 v15, 0xba000000, v17
	v_fmac_f32_e32 v14, 0xba000000, v17
	v_fmac_f32_e32 v19, 0xba000000, v17
	v_fmac_f32_e32 v18, 0xba000000, v17
	v_pk_mul_f32 v[18:19], v[16:17], v[18:19] op_sel_hi:[0,1]
	v_pk_mul_f32 v[14:15], v[16:17], v[14:15] op_sel_hi:[0,1]
	v_pk_fma_f32 v[14:15], v[64:65], v[14:15], v[68:69]
	v_pk_fma_f32 v[18:19], v[66:67], v[18:19], v[70:71]
	v_pk_fma_f32 v[8:9], v[14:15], s[62:63], v[8:9] op_sel_hi:[1,0,1]
	v_pk_fma_f32 v[10:11], v[18:19], s[62:63], v[10:11] op_sel_hi:[1,0,1]
	v_cvt_pk_bf16_f32 v14, v8, v9
	s_mov_b64 s[0:1], 0
	v_cvt_pk_bf16_f32 v15, v10, v11
	global_store_dwordx2 v[80:81], v[14:15], off offset:32
	v_add_f32_e32 v14, v8, v9
	v_add_f32_e32 v15, v10, v11
	v_add_f32_e32 v14, v14, v15
	v_pk_mul_f32 v[10:11], v[10:11], v[10:11]
	v_pk_mul_f32 v[8:9], v[8:9], v[8:9]
	v_add_f32_e32 v18, v20, v14
	v_pk_mov_b32 v[14:15], v[8:9], v[10:11] op_sel:[1,0]
	v_mov_b32_e32 v9, v11
	v_pk_add_f32 v[8:9], v[14:15], v[8:9]
	v_lshlrev_b32_e32 v10, 16, v84
	v_and_b32_e32 v11, 0xffff0000, v84
	v_lshlrev_b32_e32 v14, 16, v85
	v_and_b32_e32 v15, 0xffff0000, v85
	v_fmac_f32_e32 v11, 0xba000000, v17
	v_fmac_f32_e32 v10, 0xba000000, v17
	v_fmac_f32_e32 v15, 0xba000000, v17
	v_fmac_f32_e32 v14, 0xba000000, v17
	v_pk_mul_f32 v[14:15], v[16:17], v[14:15] op_sel_hi:[0,1]
	v_pk_mul_f32 v[10:11], v[16:17], v[10:11] op_sel_hi:[0,1]
	v_pk_fma_f32 v[10:11], v[56:57], v[10:11], v[60:61]
	v_pk_fma_f32 v[14:15], v[58:59], v[14:15], v[62:63]
	v_pk_fma_f32 v[4:5], v[10:11], s[62:63], v[4:5] op_sel_hi:[1,0,1]
	v_pk_fma_f32 v[6:7], v[14:15], s[62:63], v[6:7] op_sel_hi:[1,0,1]
	v_cvt_pk_bf16_f32 v10, v4, v5
	v_lshlrev_b32_e32 v14, 16, v83
	v_cvt_pk_bf16_f32 v11, v6, v7
	global_store_dwordx2 v[80:81], v[10:11], off offset:256
	v_add_f32_e32 v10, v4, v5
	v_add_f32_e32 v11, v6, v7
	v_add_f32_e32 v10, v10, v11
	v_add_f32_e32 v18, v18, v10
	v_lshlrev_b32_e32 v10, 16, v82
	v_and_b32_e32 v11, 0xffff0000, v82
	v_and_b32_e32 v15, 0xffff0000, v83
	v_fmac_f32_e32 v11, 0xba000000, v17
	v_fmac_f32_e32 v10, 0xba000000, v17
	v_fmac_f32_e32 v15, 0xba000000, v17
	v_fmac_f32_e32 v14, 0xba000000, v17
	v_pk_mul_f32 v[14:15], v[16:17], v[14:15] op_sel_hi:[0,1]
	v_pk_mul_f32 v[10:11], v[16:17], v[10:11] op_sel_hi:[0,1]
	v_pk_fma_f32 v[10:11], v[48:49], v[10:11], v[52:53]
	v_pk_fma_f32 v[14:15], v[50:51], v[14:15], v[54:55]
	v_pk_fma_f32 v[0:1], v[10:11], s[62:63], v[0:1] op_sel_hi:[1,0,1]
	v_pk_fma_f32 v[2:3], v[14:15], s[62:63], v[2:3] op_sel_hi:[1,0,1]
	v_cvt_pk_bf16_f32 v10, v0, v1
	v_mul_f32_e32 v14, v1, v1
	v_cvt_pk_bf16_f32 v11, v2, v3
	global_store_dwordx2 v[80:81], v[10:11], off offset:288
	v_add_f32_e32 v10, v0, v1
	v_add_f32_e32 v11, v2, v3
	v_add_f32_e32 v10, v10, v11
	v_mul_f32_e32 v11, v0, v0
	v_mul_f32_e32 v15, v2, v2
	v_mul_f32_e32 v16, v3, v3
	v_pk_add_f32 v[0:1], v[12:13], v[12:13] op_sel:[0,1] op_sel_hi:[1,0]
	v_pk_add_f32 v[2:3], v[8:9], v[8:9] op_sel:[0,1] op_sel_hi:[1,0]
	v_mov_b32_e32 v1, v11
	v_mov_b32_e32 v3, v14
	v_pk_add_f32 v[0:1], v[0:1], v[2:3]
	v_mul_f32_e32 v2, v5, v5
	v_pk_fma_f32 v[2:3], v[4:5], v[4:5], v[2:3] op_sel_hi:[1,1,0]
	v_mul_f32_e32 v4, v7, v7
	v_pk_fma_f32 v[4:5], v[6:7], v[6:7], v[4:5] op_sel_hi:[1,1,0]
	v_mov_b32_e32 v3, v15
	v_mov_b32_e32 v5, v16
	v_pk_add_f32 v[2:3], v[2:3], v[4:5]
	v_add_f32_e32 v10, v18, v10
	v_pk_add_f32 v[0:1], v[0:1], v[2:3]
	s_nop 0
	v_pk_add_f32 v[0:1], v[0:1], v[0:1] op_sel:[0,1] op_sel_hi:[1,0]
	s_nop 0
	v_mov_b32_e32 v1, v10
	s_nop 1
	v_permlane16_swap_b32_e32 v10, v1
	v_add_f32_e32 v4, v10, v1
	v_mov_b32_e32 v1, v0
	s_nop 1
	v_permlane16_swap_b32_e32 v0, v1
	v_add_f32_e32 v2, v0, v1
	v_mov_b32_e32 v5, v4
	v_mov_b32_e32 v3, v2
	s_nop 0
	v_permlane32_swap_b32_e32 v4, v5
	v_permlane32_swap_b32_e32 v2, v3
	s_and_saveexec_b64 s[12:13], s[8:9]
	s_xor_b64 s[8:9], exec, s[12:13]
	s_cbranch_execnz .LBB0_905
	s_or_saveexec_b64 s[8:9], s[8:9]
	v_mov_b64_e32 v[0:1], 0xc0000
	s_xor_b64 exec, exec, s[8:9]
	s_cbranch_execnz .LBB0_906

.LBB0_1238:
	s_or_b64 exec, exec, s[14:15]
	v_cvt_f32_u32_e32 v128, v202
	v_cvt_f32_i32_e32 v141, v203
	v_cvt_f32_u32_e32 v129, v200
	v_cvt_f32_i32_e32 v130, v201
	s_waitcnt vmcnt(12)
	v_lshlrev_b32_e32 v142, 16, v222
	v_fmac_f32_e32 v141, 0x2f800000, v128
	v_mul_f32_e32 v128, 0x3a000000, v141
	v_fmac_f32_e32 v130, 0x2f800000, v129
	v_mul_f32_e32 v128, v128, v128
	v_fma_f32 v128, v130, s94, -v128
	v_add_f32_e32 v128, 0x3727c5ac, v128
	v_rsq_f32_e32 v140, v128
	v_add_u32_e32 v128, 0x80, v176
	v_ashrrev_i32_e32 v129, 31, v128
	v_lshlrev_b64 v[130:131], 12, v[128:129]
	v_lshl_add_u64 v[130:131], s[28:29], 0, v[130:131]
	v_lshl_add_u64 v[130:131], v[186:187], 1, v[130:131]
	global_load_dwordx2 v[138:139], v[130:131], off
	global_load_dwordx2 v[136:137], v[130:131], off offset:32
	global_load_dwordx2 v[134:135], v[130:131], off offset:256
	global_load_dwordx2 v[132:133], v[130:131], off offset:288
	v_and_b32_e32 v143, 0xffff0000, v222
	v_lshlrev_b32_e32 v154, 16, v223
	v_and_b32_e32 v155, 0xffff0000, v223
	v_fmac_f32_e32 v143, 0xba000000, v141
	v_fmac_f32_e32 v142, 0xba000000, v141
	v_fmac_f32_e32 v155, 0xba000000, v141
	v_fmac_f32_e32 v154, 0xba000000, v141
	v_pk_mul_f32 v[154:155], v[140:141], v[154:155] op_sel_hi:[0,1]
	v_pk_mul_f32 v[142:143], v[140:141], v[142:143] op_sel_hi:[0,1]
	v_pk_fma_f32 v[142:143], v[72:73], v[142:143], v[76:77]
	v_pk_fma_f32 v[154:155], v[74:75], v[154:155], v[78:79]
	v_pk_fma_f32 v[124:125], v[142:143], s[62:63], v[124:125] op_sel_hi:[1,0,1]
	v_pk_fma_f32 v[126:127], v[154:155], s[62:63], v[126:127] op_sel_hi:[1,0,1]
	v_cvt_pk_bf16_f32 v142, v124, v125
	v_add_f32_e32 v129, v124, v125
	v_cvt_pk_bf16_f32 v143, v126, v127
	global_store_dwordx2 v[204:205], v[142:143], off
	v_add_f32_e32 v142, v126, v127
	v_pk_mul_f32 v[126:127], v[126:127], v[126:127]
	v_pk_mul_f32 v[124:125], v[124:125], v[124:125]
	v_add_f32_e32 v129, v129, v142
	v_pk_mov_b32 v[142:143], v[124:125], v[126:127] op_sel:[1,0]
	v_mov_b32_e32 v125, v127
	v_pk_add_f32 v[124:125], v[142:143], v[124:125]
	v_lshlrev_b32_e32 v126, 16, v218
	v_and_b32_e32 v127, 0xffff0000, v218
	v_lshlrev_b32_e32 v142, 16, v219
	v_and_b32_e32 v143, 0xffff0000, v219
	v_fmac_f32_e32 v127, 0xba000000, v141
	v_fmac_f32_e32 v126, 0xba000000, v141
	v_fmac_f32_e32 v143, 0xba000000, v141
	v_fmac_f32_e32 v142, 0xba000000, v141
	v_pk_mul_f32 v[142:143], v[140:141], v[142:143] op_sel_hi:[0,1]
	v_pk_mul_f32 v[126:127], v[140:141], v[126:127] op_sel_hi:[0,1]
	v_pk_fma_f32 v[126:127], v[64:65], v[126:127], v[68:69]
	v_pk_fma_f32 v[142:143], v[66:67], v[142:143], v[70:71]
	v_pk_fma_f32 v[120:121], v[126:127], s[62:63], v[120:121] op_sel_hi:[1,0,1]
	v_pk_fma_f32 v[122:123], v[142:143], s[62:63], v[122:123] op_sel_hi:[1,0,1]
	v_cvt_pk_bf16_f32 v126, v120, v121
	v_add_f32_e32 v129, 0, v129
	v_cvt_pk_bf16_f32 v127, v122, v123
	global_store_dwordx2 v[204:205], v[126:127], off offset:32
	v_add_f32_e32 v126, v120, v121
	v_add_f32_e32 v127, v122, v123
	v_add_f32_e32 v126, v126, v127
	v_pk_mul_f32 v[122:123], v[122:123], v[122:123]
	v_pk_mul_f32 v[120:121], v[120:121], v[120:121]
	v_add_f32_e32 v129, v129, v126
	v_pk_mov_b32 v[126:127], v[120:121], v[122:123] op_sel:[1,0]
	v_mov_b32_e32 v121, v123
	v_pk_add_f32 v[120:121], v[126:127], v[120:121]
	v_lshlrev_b32_e32 v122, 16, v212
	v_and_b32_e32 v123, 0xffff0000, v212
	v_lshlrev_b32_e32 v126, 16, v213
	v_and_b32_e32 v127, 0xffff0000, v213
	v_fmac_f32_e32 v123, 0xba000000, v141
	v_fmac_f32_e32 v122, 0xba000000, v141
	v_fmac_f32_e32 v127, 0xba000000, v141
	v_fmac_f32_e32 v126, 0xba000000, v141
	v_pk_mul_f32 v[126:127], v[140:141], v[126:127] op_sel_hi:[0,1]
	v_pk_mul_f32 v[122:123], v[140:141], v[122:123] op_sel_hi:[0,1]
	v_pk_fma_f32 v[122:123], v[56:57], v[122:123], v[60:61]
	v_pk_fma_f32 v[126:127], v[58:59], v[126:127], v[62:63]
	v_pk_fma_f32 v[116:117], v[122:123], s[62:63], v[116:117] op_sel_hi:[1,0,1]
	v_pk_fma_f32 v[118:119], v[126:127], s[62:63], v[118:119] op_sel_hi:[1,0,1]
	v_cvt_pk_bf16_f32 v122, v116, v117
	v_lshlrev_b32_e32 v126, 16, v209
	v_cvt_pk_bf16_f32 v123, v118, v119
	global_store_dwordx2 v[204:205], v[122:123], off offset:256
	v_add_f32_e32 v122, v116, v117
	v_add_f32_e32 v123, v118, v119
	v_add_f32_e32 v122, v122, v123
	v_add_f32_e32 v129, v129, v122
	v_lshlrev_b32_e32 v122, 16, v208
	v_and_b32_e32 v123, 0xffff0000, v208
	v_and_b32_e32 v127, 0xffff0000, v209
	v_fmac_f32_e32 v123, 0xba000000, v141
	v_fmac_f32_e32 v122, 0xba000000, v141
	v_fmac_f32_e32 v127, 0xba000000, v141
	v_fmac_f32_e32 v126, 0xba000000, v141
	v_pk_mul_f32 v[126:127], v[140:141], v[126:127] op_sel_hi:[0,1]
	v_pk_mul_f32 v[122:123], v[140:141], v[122:123] op_sel_hi:[0,1]
	v_pk_fma_f32 v[122:123], v[48:49], v[122:123], v[52:53]
	v_pk_fma_f32 v[126:127], v[50:51], v[126:127], v[54:55]
	v_pk_fma_f32 v[112:113], v[122:123], s[62:63], v[112:113] op_sel_hi:[1,0,1]
	v_pk_fma_f32 v[114:115], v[126:127], s[62:63], v[114:115] op_sel_hi:[1,0,1]
	v_cvt_pk_bf16_f32 v122, v112, v113
	v_mul_f32_e32 v126, v113, v113
	v_cvt_pk_bf16_f32 v123, v114, v115
	global_store_dwordx2 v[204:205], v[122:123], off offset:288
	v_add_f32_e32 v122, v112, v113
	v_add_f32_e32 v123, v114, v115
	v_add_f32_e32 v122, v122, v123
	v_add_f32_e32 v122, v129, v122
	v_mul_f32_e32 v123, v112, v112
	v_mul_f32_e32 v127, v114, v114
	v_mul_f32_e32 v129, v115, v115
	v_pk_add_f32 v[112:113], v[124:125], v[124:125] op_sel:[0,1] op_sel_hi:[1,0]
	v_pk_add_f32 v[114:115], v[120:121], v[120:121] op_sel:[0,1] op_sel_hi:[1,0]
	v_mov_b32_e32 v113, v123
	v_mov_b32_e32 v115, v126
	v_pk_add_f32 v[112:113], v[112:113], v[114:115]
	v_mul_f32_e32 v114, v117, v117
	v_pk_fma_f32 v[114:115], v[116:117], v[116:117], v[114:115] op_sel_hi:[1,1,0]
	v_mul_f32_e32 v116, v119, v119
	v_pk_fma_f32 v[116:117], v[118:119], v[118:119], v[116:117] op_sel_hi:[1,1,0]
	v_mov_b32_e32 v115, v127
	v_mov_b32_e32 v117, v129
	v_pk_add_f32 v[114:115], v[114:115], v[116:117]
	v_cmp_lt_i32_e64 s[4:5], 0, v247
	v_pk_add_f32 v[112:113], v[112:113], v[114:115]
	s_mov_b64 s[12:13], 0
	v_pk_add_f32 v[112:113], v[112:113], v[112:113] op_sel:[0,1] op_sel_hi:[1,0]
	s_nop 0
	v_mov_b32_e32 v113, v122
	s_nop 1
	v_permlane16_swap_b32_e32 v122, v113
	v_add_f32_e32 v116, v122, v113
	v_mov_b32_e32 v113, v112
	s_nop 1
	v_permlane16_swap_b32_e32 v112, v113
	v_add_f32_e32 v114, v112, v113
	v_mov_b32_e32 v117, v116
	v_mov_b32_e32 v115, v114
	s_nop 0
	v_permlane32_swap_b32_e32 v116, v117
	v_permlane32_swap_b32_e32 v114, v115
	s_and_saveexec_b64 s[14:15], s[4:5]
	s_xor_b64 s[4:5], exec, s[14:15]
	s_cbranch_execnz .LBB0_1263
	s_or_saveexec_b64 s[4:5], s[4:5]
	v_mov_b64_e32 v[112:113], 0x140000
	s_xor_b64 exec, exec, s[4:5]
	s_cbranch_execnz .LBB0_1264

.LBB0_1242:
	s_or_b64 exec, exec, s[14:15]
	s_waitcnt vmcnt(12)
	v_cvt_f32_u32_e32 v112, v198
	v_cvt_f32_i32_e32 v123, v199
	v_cvt_f32_u32_e32 v113, v196
	v_cvt_f32_i32_e32 v114, v197
	v_lshlrev_b32_e32 v124, 16, v152
	v_fmac_f32_e32 v123, 0x2f800000, v112
	v_mul_f32_e32 v112, 0x3a000000, v123
	v_fmac_f32_e32 v114, 0x2f800000, v113
	v_mul_f32_e32 v112, v112, v112
	v_fma_f32 v112, v114, s94, -v112
	v_add_f32_e32 v112, 0x3727c5ac, v112
	v_rsq_f32_e32 v122, v112
	v_or_b32_e32 v112, 16, v128
	v_ashrrev_i32_e32 v113, 31, v112
	v_lshlrev_b64 v[112:113], 12, v[112:113]
	v_lshl_add_u64 v[112:113], s[28:29], 0, v[112:113]
	v_lshl_add_u64 v[112:113], v[186:187], 1, v[112:113]
	global_load_dwordx2 v[120:121], v[112:113], off
	global_load_dwordx2 v[118:119], v[112:113], off offset:32
	global_load_dwordx2 v[116:117], v[112:113], off offset:256
	global_load_dwordx2 v[114:115], v[112:113], off offset:288
	v_and_b32_e32 v125, 0xffff0000, v152
	v_lshlrev_b32_e32 v126, 16, v153
	v_and_b32_e32 v127, 0xffff0000, v153
	v_fmac_f32_e32 v125, 0xba000000, v123
	v_fmac_f32_e32 v124, 0xba000000, v123
	v_fmac_f32_e32 v127, 0xba000000, v123
	v_fmac_f32_e32 v126, 0xba000000, v123
	v_pk_mul_f32 v[126:127], v[122:123], v[126:127] op_sel_hi:[0,1]
	v_pk_mul_f32 v[124:125], v[122:123], v[124:125] op_sel_hi:[0,1]
	v_pk_fma_f32 v[124:125], v[72:73], v[124:125], v[76:77]
	v_pk_fma_f32 v[126:127], v[74:75], v[126:127], v[78:79]
	v_pk_fma_f32 v[108:109], v[124:125], s[62:63], v[108:109] op_sel_hi:[1,0,1]
	v_pk_fma_f32 v[110:111], v[126:127], s[62:63], v[110:111] op_sel_hi:[1,0,1]
	v_cvt_pk_bf16_f32 v124, v108, v109
	v_cmp_lt_i32_e64 s[4:5], 0, v247
	v_cvt_pk_bf16_f32 v125, v110, v111
	global_store_dwordx2 v[144:145], v[124:125], off
	v_add_f32_e32 v124, v108, v109
	v_add_f32_e32 v125, v110, v111
	v_add_f32_e32 v124, v124, v125
	v_pk_mul_f32 v[110:111], v[110:111], v[110:111]
	v_pk_mul_f32 v[108:109], v[108:109], v[108:109]
	v_add_f32_e32 v126, 0, v124
	v_pk_mov_b32 v[124:125], v[108:109], v[110:111] op_sel:[1,0]
	v_mov_b32_e32 v109, v111
	v_pk_add_f32 v[108:109], v[124:125], v[108:109]
	v_lshlrev_b32_e32 v110, 16, v150
	v_and_b32_e32 v111, 0xffff0000, v150
	v_lshlrev_b32_e32 v124, 16, v151
	v_and_b32_e32 v125, 0xffff0000, v151
	v_fmac_f32_e32 v111, 0xba000000, v123
	v_fmac_f32_e32 v110, 0xba000000, v123
	v_fmac_f32_e32 v125, 0xba000000, v123
	v_fmac_f32_e32 v124, 0xba000000, v123
	v_pk_mul_f32 v[124:125], v[122:123], v[124:125] op_sel_hi:[0,1]
	v_pk_mul_f32 v[110:111], v[122:123], v[110:111] op_sel_hi:[0,1]
	v_pk_fma_f32 v[110:111], v[64:65], v[110:111], v[68:69]
	v_pk_fma_f32 v[124:125], v[66:67], v[124:125], v[70:71]
	v_pk_fma_f32 v[104:105], v[110:111], s[62:63], v[104:105] op_sel_hi:[1,0,1]
	v_pk_fma_f32 v[106:107], v[124:125], s[62:63], v[106:107] op_sel_hi:[1,0,1]
	v_cvt_pk_bf16_f32 v110, v104, v105
	s_mov_b64 s[12:13], 0
	v_cvt_pk_bf16_f32 v111, v106, v107
	global_store_dwordx2 v[144:145], v[110:111], off offset:32
	v_add_f32_e32 v110, v104, v105
	v_add_f32_e32 v111, v106, v107
	v_add_f32_e32 v110, v110, v111
	v_pk_mul_f32 v[106:107], v[106:107], v[106:107]
	v_pk_mul_f32 v[104:105], v[104:105], v[104:105]
	v_add_f32_e32 v124, v126, v110
	v_pk_mov_b32 v[110:111], v[104:105], v[106:107] op_sel:[1,0]
	v_mov_b32_e32 v105, v107
	v_pk_add_f32 v[104:105], v[110:111], v[104:105]
	v_lshlrev_b32_e32 v106, 16, v148
	v_and_b32_e32 v107, 0xffff0000, v148
	v_lshlrev_b32_e32 v110, 16, v149
	v_and_b32_e32 v111, 0xffff0000, v149
	v_fmac_f32_e32 v107, 0xba000000, v123
	v_fmac_f32_e32 v106, 0xba000000, v123
	v_fmac_f32_e32 v111, 0xba000000, v123
	v_fmac_f32_e32 v110, 0xba000000, v123
	v_pk_mul_f32 v[110:111], v[122:123], v[110:111] op_sel_hi:[0,1]
	v_pk_mul_f32 v[106:107], v[122:123], v[106:107] op_sel_hi:[0,1]
	v_pk_fma_f32 v[106:107], v[56:57], v[106:107], v[60:61]
	v_pk_fma_f32 v[110:111], v[58:59], v[110:111], v[62:63]
	v_pk_fma_f32 v[100:101], v[106:107], s[62:63], v[100:101] op_sel_hi:[1,0,1]
	v_pk_fma_f32 v[102:103], v[110:111], s[62:63], v[102:103] op_sel_hi:[1,0,1]
	v_cvt_pk_bf16_f32 v106, v100, v101
	v_lshlrev_b32_e32 v110, 16, v147
	v_cvt_pk_bf16_f32 v107, v102, v103
	global_store_dwordx2 v[144:145], v[106:107], off offset:256
	v_add_f32_e32 v106, v100, v101
	v_add_f32_e32 v107, v102, v103
	v_add_f32_e32 v106, v106, v107
	v_add_f32_e32 v124, v124, v106
	v_lshlrev_b32_e32 v106, 16, v146
	v_and_b32_e32 v107, 0xffff0000, v146
	v_and_b32_e32 v111, 0xffff0000, v147
	v_fmac_f32_e32 v107, 0xba000000, v123
	v_fmac_f32_e32 v106, 0xba000000, v123
	v_fmac_f32_e32 v111, 0xba000000, v123
	v_fmac_f32_e32 v110, 0xba000000, v123
	v_pk_mul_f32 v[110:111], v[122:123], v[110:111] op_sel_hi:[0,1]
	v_pk_mul_f32 v[106:107], v[122:123], v[106:107] op_sel_hi:[0,1]
	v_pk_fma_f32 v[106:107], v[48:49], v[106:107], v[52:53]
	v_pk_fma_f32 v[110:111], v[50:51], v[110:111], v[54:55]
	v_pk_fma_f32 v[96:97], v[106:107], s[62:63], v[96:97] op_sel_hi:[1,0,1]
	v_pk_fma_f32 v[98:99], v[110:111], s[62:63], v[98:99] op_sel_hi:[1,0,1]
	v_cvt_pk_bf16_f32 v106, v96, v97
	v_mul_f32_e32 v110, v97, v97
	v_cvt_pk_bf16_f32 v107, v98, v99
	global_store_dwordx2 v[144:145], v[106:107], off offset:288
	v_add_f32_e32 v106, v96, v97
	v_add_f32_e32 v107, v98, v99
	v_add_f32_e32 v106, v106, v107
	v_mul_f32_e32 v107, v96, v96
	v_mul_f32_e32 v111, v98, v98
	v_mul_f32_e32 v122, v99, v99
	v_pk_add_f32 v[96:97], v[108:109], v[108:109] op_sel:[0,1] op_sel_hi:[1,0]
	v_pk_add_f32 v[98:99], v[104:105], v[104:105] op_sel:[0,1] op_sel_hi:[1,0]
	v_mov_b32_e32 v97, v107
	v_mov_b32_e32 v99, v110
	v_pk_add_f32 v[96:97], v[96:97], v[98:99]
	v_mul_f32_e32 v98, v101, v101
	v_pk_fma_f32 v[98:99], v[100:101], v[100:101], v[98:99] op_sel_hi:[1,1,0]
	v_mul_f32_e32 v100, v103, v103
	v_pk_fma_f32 v[100:101], v[102:103], v[102:103], v[100:101] op_sel_hi:[1,1,0]
	v_mov_b32_e32 v99, v111
	v_mov_b32_e32 v101, v122
	v_pk_add_f32 v[98:99], v[98:99], v[100:101]
	v_add_f32_e32 v106, v124, v106
	v_pk_add_f32 v[96:97], v[96:97], v[98:99]
	s_nop 0
	v_pk_add_f32 v[96:97], v[96:97], v[96:97] op_sel:[0,1] op_sel_hi:[1,0]
	s_nop 0
	v_mov_b32_e32 v97, v106
	s_nop 1
	v_permlane16_swap_b32_e32 v106, v97
	v_add_f32_e32 v100, v106, v97
	v_mov_b32_e32 v97, v96
	s_nop 1
	v_permlane16_swap_b32_e32 v96, v97
	v_add_f32_e32 v98, v96, v97
	v_mov_b32_e32 v101, v100
	v_mov_b32_e32 v99, v98
	s_nop 0
	v_permlane32_swap_b32_e32 v100, v101
	v_permlane32_swap_b32_e32 v98, v99
	s_and_saveexec_b64 s[14:15], s[4:5]
	s_xor_b64 s[4:5], exec, s[14:15]
	s_cbranch_execnz .LBB0_1265
	s_or_saveexec_b64 s[4:5], s[4:5]
	v_mov_b64_e32 v[96:97], 0x140000
	s_xor_b64 exec, exec, s[4:5]
	s_cbranch_execnz .LBB0_1266

.LBB0_1246:
	s_or_b64 exec, exec, s[14:15]
	v_cvt_f32_u32_e32 v96, v194
	v_cvt_f32_i32_e32 v107, v195
	v_cvt_f32_u32_e32 v97, v192
	v_cvt_f32_i32_e32 v98, v193
	s_waitcnt vmcnt(12)
	v_lshlrev_b32_e32 v108, 16, v138
	v_fmac_f32_e32 v107, 0x2f800000, v96
	v_mul_f32_e32 v96, 0x3a000000, v107
	v_fmac_f32_e32 v98, 0x2f800000, v97
	v_mul_f32_e32 v96, v96, v96
	v_fma_f32 v96, v98, s94, -v96
	v_add_f32_e32 v96, 0x3727c5ac, v96
	v_rsq_f32_e32 v106, v96
	v_or_b32_e32 v96, 32, v128
	v_ashrrev_i32_e32 v97, 31, v96
	v_lshlrev_b64 v[96:97], 12, v[96:97]
	v_lshl_add_u64 v[96:97], s[28:29], 0, v[96:97]
	v_lshl_add_u64 v[96:97], v[186:187], 1, v[96:97]
	global_load_dwordx2 v[104:105], v[96:97], off
	global_load_dwordx2 v[102:103], v[96:97], off offset:32
	global_load_dwordx2 v[100:101], v[96:97], off offset:256
	global_load_dwordx2 v[98:99], v[96:97], off offset:288
	v_and_b32_e32 v109, 0xffff0000, v138
	v_lshlrev_b32_e32 v110, 16, v139
	v_and_b32_e32 v111, 0xffff0000, v139
	v_fmac_f32_e32 v109, 0xba000000, v107
	v_fmac_f32_e32 v108, 0xba000000, v107
	v_fmac_f32_e32 v111, 0xba000000, v107
	v_fmac_f32_e32 v110, 0xba000000, v107
	v_pk_mul_f32 v[110:111], v[106:107], v[110:111] op_sel_hi:[0,1]
	v_pk_mul_f32 v[108:109], v[106:107], v[108:109] op_sel_hi:[0,1]
	v_pk_fma_f32 v[108:109], v[72:73], v[108:109], v[76:77]
	v_pk_fma_f32 v[110:111], v[74:75], v[110:111], v[78:79]
	v_pk_fma_f32 v[92:93], v[108:109], s[62:63], v[92:93] op_sel_hi:[1,0,1]
	v_pk_fma_f32 v[94:95], v[110:111], s[62:63], v[94:95] op_sel_hi:[1,0,1]
	v_cvt_pk_bf16_f32 v108, v92, v93
	v_cmp_lt_i32_e64 s[4:5], 0, v247
	v_cvt_pk_bf16_f32 v109, v94, v95
	global_store_dwordx2 v[130:131], v[108:109], off
	v_add_f32_e32 v108, v92, v93
	v_add_f32_e32 v109, v94, v95
	v_add_f32_e32 v108, v108, v109
	v_pk_mul_f32 v[94:95], v[94:95], v[94:95]
	v_pk_mul_f32 v[92:93], v[92:93], v[92:93]
	v_add_f32_e32 v110, 0, v108
	v_pk_mov_b32 v[108:109], v[92:93], v[94:95] op_sel:[1,0]
	v_mov_b32_e32 v93, v95
	v_pk_add_f32 v[92:93], v[108:109], v[92:93]
	v_lshlrev_b32_e32 v94, 16, v136
	v_and_b32_e32 v95, 0xffff0000, v136
	v_lshlrev_b32_e32 v108, 16, v137
	v_and_b32_e32 v109, 0xffff0000, v137
	v_fmac_f32_e32 v95, 0xba000000, v107
	v_fmac_f32_e32 v94, 0xba000000, v107
	v_fmac_f32_e32 v109, 0xba000000, v107
	v_fmac_f32_e32 v108, 0xba000000, v107
	v_pk_mul_f32 v[108:109], v[106:107], v[108:109] op_sel_hi:[0,1]
	v_pk_mul_f32 v[94:95], v[106:107], v[94:95] op_sel_hi:[0,1]
	v_pk_fma_f32 v[94:95], v[64:65], v[94:95], v[68:69]
	v_pk_fma_f32 v[108:109], v[66:67], v[108:109], v[70:71]
	v_pk_fma_f32 v[88:89], v[94:95], s[62:63], v[88:89] op_sel_hi:[1,0,1]
	v_pk_fma_f32 v[90:91], v[108:109], s[62:63], v[90:91] op_sel_hi:[1,0,1]
	v_cvt_pk_bf16_f32 v94, v88, v89
	s_mov_b64 s[12:13], 0
	v_cvt_pk_bf16_f32 v95, v90, v91
	global_store_dwordx2 v[130:131], v[94:95], off offset:32
	v_add_f32_e32 v94, v88, v89
	v_add_f32_e32 v95, v90, v91
	v_add_f32_e32 v94, v94, v95
	v_pk_mul_f32 v[90:91], v[90:91], v[90:91]
	v_pk_mul_f32 v[88:89], v[88:89], v[88:89]
	v_add_f32_e32 v108, v110, v94
	v_pk_mov_b32 v[94:95], v[88:89], v[90:91] op_sel:[1,0]
	v_mov_b32_e32 v89, v91
	v_pk_add_f32 v[88:89], v[94:95], v[88:89]
	v_lshlrev_b32_e32 v90, 16, v134
	v_and_b32_e32 v91, 0xffff0000, v134
	v_lshlrev_b32_e32 v94, 16, v135
	v_and_b32_e32 v95, 0xffff0000, v135
	v_fmac_f32_e32 v91, 0xba000000, v107
	v_fmac_f32_e32 v90, 0xba000000, v107
	v_fmac_f32_e32 v95, 0xba000000, v107
	v_fmac_f32_e32 v94, 0xba000000, v107
	v_pk_mul_f32 v[94:95], v[106:107], v[94:95] op_sel_hi:[0,1]
	v_pk_mul_f32 v[90:91], v[106:107], v[90:91] op_sel_hi:[0,1]
	v_pk_fma_f32 v[90:91], v[56:57], v[90:91], v[60:61]
	v_pk_fma_f32 v[94:95], v[58:59], v[94:95], v[62:63]
	v_pk_fma_f32 v[84:85], v[90:91], s[62:63], v[84:85] op_sel_hi:[1,0,1]
	v_pk_fma_f32 v[86:87], v[94:95], s[62:63], v[86:87] op_sel_hi:[1,0,1]
	v_cvt_pk_bf16_f32 v90, v84, v85
	v_lshlrev_b32_e32 v94, 16, v133
	v_cvt_pk_bf16_f32 v91, v86, v87
	global_store_dwordx2 v[130:131], v[90:91], off offset:256
	v_add_f32_e32 v90, v84, v85
	v_add_f32_e32 v91, v86, v87
	v_add_f32_e32 v90, v90, v91
	v_add_f32_e32 v108, v108, v90
	v_lshlrev_b32_e32 v90, 16, v132
	v_and_b32_e32 v91, 0xffff0000, v132
	v_and_b32_e32 v95, 0xffff0000, v133
	v_fmac_f32_e32 v91, 0xba000000, v107
	v_fmac_f32_e32 v90, 0xba000000, v107
	v_fmac_f32_e32 v95, 0xba000000, v107
	v_fmac_f32_e32 v94, 0xba000000, v107
	v_pk_mul_f32 v[94:95], v[106:107], v[94:95] op_sel_hi:[0,1]
	v_pk_mul_f32 v[90:91], v[106:107], v[90:91] op_sel_hi:[0,1]
	v_pk_fma_f32 v[90:91], v[48:49], v[90:91], v[52:53]
	v_pk_fma_f32 v[94:95], v[50:51], v[94:95], v[54:55]
	v_pk_fma_f32 v[80:81], v[90:91], s[62:63], v[80:81] op_sel_hi:[1,0,1]
	v_pk_fma_f32 v[82:83], v[94:95], s[62:63], v[82:83] op_sel_hi:[1,0,1]
	v_cvt_pk_bf16_f32 v90, v80, v81
	v_mul_f32_e32 v94, v81, v81
	v_cvt_pk_bf16_f32 v91, v82, v83
	global_store_dwordx2 v[130:131], v[90:91], off offset:288
	v_add_f32_e32 v90, v80, v81
	v_add_f32_e32 v91, v82, v83
	v_add_f32_e32 v90, v90, v91
	v_mul_f32_e32 v91, v80, v80
	v_mul_f32_e32 v95, v82, v82
	v_mul_f32_e32 v106, v83, v83
	v_pk_add_f32 v[80:81], v[92:93], v[92:93] op_sel:[0,1] op_sel_hi:[1,0]
	v_pk_add_f32 v[82:83], v[88:89], v[88:89] op_sel:[0,1] op_sel_hi:[1,0]
	v_mov_b32_e32 v81, v91
	v_mov_b32_e32 v83, v94
	v_pk_add_f32 v[80:81], v[80:81], v[82:83]
	v_mul_f32_e32 v82, v85, v85
	v_pk_fma_f32 v[82:83], v[84:85], v[84:85], v[82:83] op_sel_hi:[1,1,0]
	v_mul_f32_e32 v84, v87, v87
	v_pk_fma_f32 v[84:85], v[86:87], v[86:87], v[84:85] op_sel_hi:[1,1,0]
	v_mov_b32_e32 v83, v95
	v_mov_b32_e32 v85, v106
	v_pk_add_f32 v[82:83], v[82:83], v[84:85]
	v_add_f32_e32 v90, v108, v90
	v_pk_add_f32 v[80:81], v[80:81], v[82:83]
	s_nop 0
	v_pk_add_f32 v[80:81], v[80:81], v[80:81] op_sel:[0,1] op_sel_hi:[1,0]
	s_nop 0
	v_mov_b32_e32 v81, v90
	s_nop 1
	v_permlane16_swap_b32_e32 v90, v81
	v_add_f32_e32 v84, v90, v81
	v_mov_b32_e32 v81, v80
	s_nop 1
	v_permlane16_swap_b32_e32 v80, v81
	v_add_f32_e32 v82, v80, v81
	v_mov_b32_e32 v85, v84
	v_mov_b32_e32 v83, v82
	s_nop 0
	v_permlane32_swap_b32_e32 v84, v85
	v_permlane32_swap_b32_e32 v82, v83
	s_and_saveexec_b64 s[14:15], s[4:5]
	s_xor_b64 s[4:5], exec, s[14:15]
	s_cbranch_execnz .LBB0_1267
	s_or_saveexec_b64 s[4:5], s[4:5]
	v_mov_b64_e32 v[80:81], 0x140000
	s_xor_b64 exec, exec, s[4:5]
	s_cbranch_execnz .LBB0_1268

.LBB0_1250:
	s_or_b64 exec, exec, s[14:15]
	s_waitcnt vmcnt(12)
	v_cvt_f32_u32_e32 v80, v190
	v_cvt_f32_i32_e32 v91, v191
	v_cvt_f32_u32_e32 v81, v188
	v_cvt_f32_i32_e32 v82, v189
	v_lshlrev_b32_e32 v92, 16, v120
	v_fmac_f32_e32 v91, 0x2f800000, v80
	v_mul_f32_e32 v80, 0x3a000000, v91
	v_fmac_f32_e32 v82, 0x2f800000, v81
	v_mul_f32_e32 v80, v80, v80
	v_fma_f32 v80, v82, s94, -v80
	v_add_f32_e32 v80, 0x3727c5ac, v80
	v_rsq_f32_e32 v90, v80
	v_or_b32_e32 v80, 48, v128
	v_ashrrev_i32_e32 v81, 31, v80
	v_lshlrev_b64 v[80:81], 12, v[80:81]
	v_lshl_add_u64 v[80:81], s[28:29], 0, v[80:81]
	v_lshl_add_u64 v[80:81], v[186:187], 1, v[80:81]
	global_load_dwordx2 v[88:89], v[80:81], off
	global_load_dwordx2 v[86:87], v[80:81], off offset:32
	global_load_dwordx2 v[84:85], v[80:81], off offset:256
	global_load_dwordx2 v[82:83], v[80:81], off offset:288
	v_and_b32_e32 v93, 0xffff0000, v120
	v_lshlrev_b32_e32 v94, 16, v121
	v_and_b32_e32 v95, 0xffff0000, v121
	v_fmac_f32_e32 v93, 0xba000000, v91
	v_fmac_f32_e32 v92, 0xba000000, v91
	v_fmac_f32_e32 v95, 0xba000000, v91
	v_fmac_f32_e32 v94, 0xba000000, v91
	v_pk_mul_f32 v[94:95], v[90:91], v[94:95] op_sel_hi:[0,1]
	v_pk_mul_f32 v[92:93], v[90:91], v[92:93] op_sel_hi:[0,1]
	v_pk_fma_f32 v[92:93], v[72:73], v[92:93], v[76:77]
	v_pk_fma_f32 v[94:95], v[74:75], v[94:95], v[78:79]
	v_pk_fma_f32 v[44:45], v[92:93], s[62:63], v[44:45] op_sel_hi:[1,0,1]
	v_pk_fma_f32 v[46:47], v[94:95], s[62:63], v[46:47] op_sel_hi:[1,0,1]
	v_cvt_pk_bf16_f32 v92, v44, v45
	v_cmp_lt_i32_e64 s[4:5], 0, v247
	v_cvt_pk_bf16_f32 v93, v46, v47
	global_store_dwordx2 v[112:113], v[92:93], off
	v_add_f32_e32 v92, v44, v45
	v_add_f32_e32 v93, v46, v47
	v_add_f32_e32 v92, v92, v93
	v_pk_mul_f32 v[46:47], v[46:47], v[46:47]
	v_pk_mul_f32 v[44:45], v[44:45], v[44:45]
	v_add_f32_e32 v94, 0, v92
	v_pk_mov_b32 v[92:93], v[44:45], v[46:47] op_sel:[1,0]
	v_mov_b32_e32 v45, v47
	v_pk_add_f32 v[44:45], v[92:93], v[44:45]
	v_lshlrev_b32_e32 v46, 16, v118
	v_and_b32_e32 v47, 0xffff0000, v118
	v_lshlrev_b32_e32 v92, 16, v119
	v_and_b32_e32 v93, 0xffff0000, v119
	v_fmac_f32_e32 v47, 0xba000000, v91
	v_fmac_f32_e32 v46, 0xba000000, v91
	v_fmac_f32_e32 v93, 0xba000000, v91
	v_fmac_f32_e32 v92, 0xba000000, v91
	v_pk_mul_f32 v[92:93], v[90:91], v[92:93] op_sel_hi:[0,1]
	v_pk_mul_f32 v[46:47], v[90:91], v[46:47] op_sel_hi:[0,1]
	v_pk_fma_f32 v[46:47], v[64:65], v[46:47], v[68:69]
	v_pk_fma_f32 v[92:93], v[66:67], v[92:93], v[70:71]
	v_pk_fma_f32 v[40:41], v[46:47], s[62:63], v[40:41] op_sel_hi:[1,0,1]
	v_pk_fma_f32 v[42:43], v[92:93], s[62:63], v[42:43] op_sel_hi:[1,0,1]
	v_cvt_pk_bf16_f32 v46, v40, v41
	s_mov_b64 s[12:13], 0
	v_cvt_pk_bf16_f32 v47, v42, v43
	global_store_dwordx2 v[112:113], v[46:47], off offset:32
	v_add_f32_e32 v46, v40, v41
	v_add_f32_e32 v47, v42, v43
	v_add_f32_e32 v46, v46, v47
	v_pk_mul_f32 v[42:43], v[42:43], v[42:43]
	v_pk_mul_f32 v[40:41], v[40:41], v[40:41]
	v_add_f32_e32 v92, v94, v46
	v_pk_mov_b32 v[46:47], v[40:41], v[42:43] op_sel:[1,0]
	v_mov_b32_e32 v41, v43
	v_pk_add_f32 v[40:41], v[46:47], v[40:41]
	v_lshlrev_b32_e32 v42, 16, v116
	v_and_b32_e32 v43, 0xffff0000, v116
	v_lshlrev_b32_e32 v46, 16, v117
	v_and_b32_e32 v47, 0xffff0000, v117
	v_fmac_f32_e32 v43, 0xba000000, v91
	v_fmac_f32_e32 v42, 0xba000000, v91
	v_fmac_f32_e32 v47, 0xba000000, v91
	v_fmac_f32_e32 v46, 0xba000000, v91
	v_pk_mul_f32 v[46:47], v[90:91], v[46:47] op_sel_hi:[0,1]
	v_pk_mul_f32 v[42:43], v[90:91], v[42:43] op_sel_hi:[0,1]
	v_pk_fma_f32 v[42:43], v[56:57], v[42:43], v[60:61]
	v_pk_fma_f32 v[46:47], v[58:59], v[46:47], v[62:63]
	v_pk_fma_f32 v[36:37], v[42:43], s[62:63], v[36:37] op_sel_hi:[1,0,1]
	v_pk_fma_f32 v[38:39], v[46:47], s[62:63], v[38:39] op_sel_hi:[1,0,1]
	v_cvt_pk_bf16_f32 v42, v36, v37
	v_lshlrev_b32_e32 v46, 16, v115
	v_cvt_pk_bf16_f32 v43, v38, v39
	global_store_dwordx2 v[112:113], v[42:43], off offset:256
	v_add_f32_e32 v42, v36, v37
	v_add_f32_e32 v43, v38, v39
	v_add_f32_e32 v42, v42, v43
	v_add_f32_e32 v92, v92, v42
	v_lshlrev_b32_e32 v42, 16, v114
	v_and_b32_e32 v43, 0xffff0000, v114
	v_and_b32_e32 v47, 0xffff0000, v115
	v_fmac_f32_e32 v43, 0xba000000, v91
	v_fmac_f32_e32 v42, 0xba000000, v91
	v_fmac_f32_e32 v47, 0xba000000, v91
	v_fmac_f32_e32 v46, 0xba000000, v91
	v_pk_mul_f32 v[46:47], v[90:91], v[46:47] op_sel_hi:[0,1]
	v_pk_mul_f32 v[42:43], v[90:91], v[42:43] op_sel_hi:[0,1]
	v_pk_fma_f32 v[42:43], v[48:49], v[42:43], v[52:53]
	v_pk_fma_f32 v[46:47], v[50:51], v[46:47], v[54:55]
	v_pk_fma_f32 v[32:33], v[42:43], s[62:63], v[32:33] op_sel_hi:[1,0,1]
	v_pk_fma_f32 v[34:35], v[46:47], s[62:63], v[34:35] op_sel_hi:[1,0,1]
	v_cvt_pk_bf16_f32 v42, v32, v33
	v_mul_f32_e32 v46, v33, v33
	v_cvt_pk_bf16_f32 v43, v34, v35
	global_store_dwordx2 v[112:113], v[42:43], off offset:288
	v_add_f32_e32 v42, v32, v33
	v_add_f32_e32 v43, v34, v35
	v_add_f32_e32 v42, v42, v43
	v_mul_f32_e32 v43, v32, v32
	v_mul_f32_e32 v47, v34, v34
	v_mul_f32_e32 v90, v35, v35
	v_pk_add_f32 v[32:33], v[44:45], v[44:45] op_sel:[0,1] op_sel_hi:[1,0]
	v_pk_add_f32 v[34:35], v[40:41], v[40:41] op_sel:[0,1] op_sel_hi:[1,0]
	v_mov_b32_e32 v33, v43
	v_mov_b32_e32 v35, v46
	v_pk_add_f32 v[32:33], v[32:33], v[34:35]
	v_mul_f32_e32 v34, v37, v37
	v_pk_fma_f32 v[34:35], v[36:37], v[36:37], v[34:35] op_sel_hi:[1,1,0]
	v_mul_f32_e32 v36, v39, v39
	v_pk_fma_f32 v[36:37], v[38:39], v[38:39], v[36:37] op_sel_hi:[1,1,0]
	v_mov_b32_e32 v35, v47
	v_mov_b32_e32 v37, v90
	v_pk_add_f32 v[34:35], v[34:35], v[36:37]
	v_add_f32_e32 v42, v92, v42
	v_pk_add_f32 v[32:33], v[32:33], v[34:35]
	s_nop 0
	v_pk_add_f32 v[32:33], v[32:33], v[32:33] op_sel:[0,1] op_sel_hi:[1,0]
	s_nop 0
	v_mov_b32_e32 v33, v42
	s_nop 1
	v_permlane16_swap_b32_e32 v42, v33
	v_add_f32_e32 v36, v42, v33
	v_mov_b32_e32 v33, v32
	s_nop 1
	v_permlane16_swap_b32_e32 v32, v33
	v_add_f32_e32 v34, v32, v33
	v_mov_b32_e32 v37, v36
	v_mov_b32_e32 v35, v34
	s_nop 0
	v_permlane32_swap_b32_e32 v36, v37
	v_permlane32_swap_b32_e32 v34, v35
	s_and_saveexec_b64 s[14:15], s[4:5]
	s_xor_b64 s[4:5], exec, s[14:15]
	s_cbranch_execnz .LBB0_1269
	s_or_saveexec_b64 s[4:5], s[4:5]
	v_mov_b64_e32 v[32:33], 0x140000
	s_xor_b64 exec, exec, s[4:5]
	s_cbranch_execnz .LBB0_1270

.LBB0_1254:
	s_or_b64 exec, exec, s[14:15]
	v_cvt_f32_u32_e32 v32, v184
	v_cvt_f32_i32_e32 v33, v185
	v_cvt_f32_u32_e32 v34, v182
	v_cvt_f32_i32_e32 v35, v183
	s_waitcnt vmcnt(12)
	v_lshlrev_b32_e32 v36, 16, v105
	v_fmac_f32_e32 v33, 0x2f800000, v32
	v_mul_f32_e32 v32, 0x3a000000, v33
	v_fmac_f32_e32 v35, 0x2f800000, v34
	v_mul_f32_e32 v32, v32, v32
	v_fma_f32 v32, v35, s94, -v32
	v_add_f32_e32 v32, 0x3727c5ac, v32
	v_rsq_f32_e32 v32, v32
	v_lshlrev_b32_e32 v34, 16, v104
	v_and_b32_e32 v35, 0xffff0000, v104
	v_and_b32_e32 v37, 0xffff0000, v105
	v_fmac_f32_e32 v35, 0xba000000, v33
	v_fmac_f32_e32 v34, 0xba000000, v33
	v_fmac_f32_e32 v37, 0xba000000, v33
	v_fmac_f32_e32 v36, 0xba000000, v33
	v_pk_mul_f32 v[36:37], v[32:33], v[36:37] op_sel_hi:[0,1]
	v_pk_mul_f32 v[34:35], v[32:33], v[34:35] op_sel_hi:[0,1]
	v_pk_fma_f32 v[34:35], v[72:73], v[34:35], v[76:77]
	v_pk_fma_f32 v[36:37], v[74:75], v[36:37], v[78:79]
	v_pk_fma_f32 v[28:29], v[34:35], s[62:63], v[28:29] op_sel_hi:[1,0,1]
	v_pk_fma_f32 v[30:31], v[36:37], s[62:63], v[30:31] op_sel_hi:[1,0,1]
	v_cvt_pk_bf16_f32 v34, v28, v29
	v_cmp_lt_i32_e64 s[4:5], 0, v247
	v_cvt_pk_bf16_f32 v35, v30, v31
	global_store_dwordx2 v[96:97], v[34:35], off
	v_add_f32_e32 v34, v28, v29
	v_add_f32_e32 v35, v30, v31
	v_add_f32_e32 v34, v34, v35
	v_pk_mul_f32 v[30:31], v[30:31], v[30:31]
	v_pk_mul_f32 v[28:29], v[28:29], v[28:29]
	v_add_f32_e32 v36, 0, v34
	v_pk_mov_b32 v[34:35], v[28:29], v[30:31] op_sel:[1,0]
	v_mov_b32_e32 v29, v31
	v_pk_add_f32 v[28:29], v[34:35], v[28:29]
	v_lshlrev_b32_e32 v30, 16, v102
	v_and_b32_e32 v31, 0xffff0000, v102
	v_lshlrev_b32_e32 v34, 16, v103
	v_and_b32_e32 v35, 0xffff0000, v103
	v_fmac_f32_e32 v31, 0xba000000, v33
	v_fmac_f32_e32 v30, 0xba000000, v33
	v_fmac_f32_e32 v35, 0xba000000, v33
	v_fmac_f32_e32 v34, 0xba000000, v33
	v_pk_mul_f32 v[34:35], v[32:33], v[34:35] op_sel_hi:[0,1]
	v_pk_mul_f32 v[30:31], v[32:33], v[30:31] op_sel_hi:[0,1]
	v_pk_fma_f32 v[30:31], v[64:65], v[30:31], v[68:69]
	v_pk_fma_f32 v[34:35], v[66:67], v[34:35], v[70:71]
	v_pk_fma_f32 v[24:25], v[30:31], s[62:63], v[24:25] op_sel_hi:[1,0,1]
	v_pk_fma_f32 v[26:27], v[34:35], s[62:63], v[26:27] op_sel_hi:[1,0,1]
	v_cvt_pk_bf16_f32 v30, v24, v25
	s_mov_b64 s[12:13], 0
	v_cvt_pk_bf16_f32 v31, v26, v27
	global_store_dwordx2 v[96:97], v[30:31], off offset:32
	v_add_f32_e32 v30, v24, v25
	v_add_f32_e32 v31, v26, v27
	v_add_f32_e32 v30, v30, v31
	v_pk_mul_f32 v[26:27], v[26:27], v[26:27]
	v_pk_mul_f32 v[24:25], v[24:25], v[24:25]
	v_add_f32_e32 v34, v36, v30
	v_pk_mov_b32 v[30:31], v[24:25], v[26:27] op_sel:[1,0]
	v_mov_b32_e32 v25, v27
	v_pk_add_f32 v[24:25], v[30:31], v[24:25]
	v_lshlrev_b32_e32 v26, 16, v100
	v_and_b32_e32 v27, 0xffff0000, v100
	v_lshlrev_b32_e32 v30, 16, v101
	v_and_b32_e32 v31, 0xffff0000, v101
	v_fmac_f32_e32 v27, 0xba000000, v33
	v_fmac_f32_e32 v26, 0xba000000, v33
	v_fmac_f32_e32 v31, 0xba000000, v33
	v_fmac_f32_e32 v30, 0xba000000, v33
	v_pk_mul_f32 v[30:31], v[32:33], v[30:31] op_sel_hi:[0,1]
	v_pk_mul_f32 v[26:27], v[32:33], v[26:27] op_sel_hi:[0,1]
	v_pk_fma_f32 v[26:27], v[56:57], v[26:27], v[60:61]
	v_pk_fma_f32 v[30:31], v[58:59], v[30:31], v[62:63]
	v_pk_fma_f32 v[20:21], v[26:27], s[62:63], v[20:21] op_sel_hi:[1,0,1]
	v_pk_fma_f32 v[22:23], v[30:31], s[62:63], v[22:23] op_sel_hi:[1,0,1]
	v_cvt_pk_bf16_f32 v26, v20, v21
	v_lshlrev_b32_e32 v30, 16, v99
	v_cvt_pk_bf16_f32 v27, v22, v23
	global_store_dwordx2 v[96:97], v[26:27], off offset:256
	v_add_f32_e32 v26, v20, v21
	v_add_f32_e32 v27, v22, v23
	v_add_f32_e32 v26, v26, v27
	v_add_f32_e32 v34, v34, v26
	v_lshlrev_b32_e32 v26, 16, v98
	v_and_b32_e32 v27, 0xffff0000, v98
	v_and_b32_e32 v31, 0xffff0000, v99
	v_fmac_f32_e32 v27, 0xba000000, v33
	v_fmac_f32_e32 v26, 0xba000000, v33
	v_fmac_f32_e32 v31, 0xba000000, v33
	v_fmac_f32_e32 v30, 0xba000000, v33
	v_pk_mul_f32 v[30:31], v[32:33], v[30:31] op_sel_hi:[0,1]
	v_pk_mul_f32 v[26:27], v[32:33], v[26:27] op_sel_hi:[0,1]
	v_pk_fma_f32 v[26:27], v[48:49], v[26:27], v[52:53]
	v_pk_fma_f32 v[30:31], v[50:51], v[30:31], v[54:55]
	v_pk_fma_f32 v[16:17], v[26:27], s[62:63], v[16:17] op_sel_hi:[1,0,1]
	v_pk_fma_f32 v[18:19], v[30:31], s[62:63], v[18:19] op_sel_hi:[1,0,1]
	v_cvt_pk_bf16_f32 v26, v16, v17
	v_mul_f32_e32 v30, v17, v17
	v_cvt_pk_bf16_f32 v27, v18, v19
	global_store_dwordx2 v[96:97], v[26:27], off offset:288
	v_add_f32_e32 v26, v16, v17
	v_add_f32_e32 v27, v18, v19
	v_add_f32_e32 v26, v26, v27
	v_mul_f32_e32 v27, v16, v16
	v_mul_f32_e32 v31, v18, v18
	v_mul_f32_e32 v32, v19, v19
	v_pk_add_f32 v[16:17], v[28:29], v[28:29] op_sel:[0,1] op_sel_hi:[1,0]
	v_pk_add_f32 v[18:19], v[24:25], v[24:25] op_sel:[0,1] op_sel_hi:[1,0]
	v_mov_b32_e32 v17, v27
	v_mov_b32_e32 v19, v30
	v_pk_add_f32 v[16:17], v[16:17], v[18:19]
	v_mul_f32_e32 v18, v21, v21
	v_pk_fma_f32 v[18:19], v[20:21], v[20:21], v[18:19] op_sel_hi:[1,1,0]
	v_mul_f32_e32 v20, v23, v23
	v_pk_fma_f32 v[20:21], v[22:23], v[22:23], v[20:21] op_sel_hi:[1,1,0]
	v_mov_b32_e32 v19, v31
	v_mov_b32_e32 v21, v32
	v_pk_add_f32 v[18:19], v[18:19], v[20:21]
	v_add_f32_e32 v26, v34, v26
	v_pk_add_f32 v[16:17], v[16:17], v[18:19]
	s_nop 0
	v_pk_add_f32 v[16:17], v[16:17], v[16:17] op_sel:[0,1] op_sel_hi:[1,0]
	s_nop 0
	v_mov_b32_e32 v17, v26
	s_nop 1
	v_permlane16_swap_b32_e32 v26, v17
	v_add_f32_e32 v20, v26, v17
	v_mov_b32_e32 v17, v16
	s_nop 1
	v_permlane16_swap_b32_e32 v16, v17
	v_add_f32_e32 v18, v16, v17
	v_mov_b32_e32 v21, v20
	v_mov_b32_e32 v19, v18
	s_nop 0
	v_permlane32_swap_b32_e32 v20, v21
	v_permlane32_swap_b32_e32 v18, v19
	s_and_saveexec_b64 s[14:15], s[4:5]
	s_xor_b64 s[4:5], exec, s[14:15]
	s_cbranch_execnz .LBB0_1271
	s_or_saveexec_b64 s[4:5], s[4:5]
	v_mov_b64_e32 v[16:17], 0x140000
	s_xor_b64 exec, exec, s[4:5]
	s_cbranch_execnz .LBB0_1272

.LBB0_1258:
	s_or_b64 exec, exec, s[14:15]
	s_waitcnt vmcnt(8)
	v_cvt_f32_u32_e32 v16, v180
	v_cvt_f32_i32_e32 v17, v181
	v_cvt_f32_u32_e32 v18, v178
	v_cvt_f32_i32_e32 v19, v179
	v_lshlrev_b32_e32 v20, 16, v89
	v_fmac_f32_e32 v17, 0x2f800000, v16
	v_mul_f32_e32 v16, 0x3a000000, v17
	v_fmac_f32_e32 v19, 0x2f800000, v18
	v_mul_f32_e32 v16, v16, v16
	v_fma_f32 v16, v19, s94, -v16
	v_add_f32_e32 v16, 0x3727c5ac, v16
	v_rsq_f32_e32 v16, v16
	v_lshlrev_b32_e32 v18, 16, v88
	v_and_b32_e32 v19, 0xffff0000, v88
	v_and_b32_e32 v21, 0xffff0000, v89
	v_fmac_f32_e32 v19, 0xba000000, v17
	v_fmac_f32_e32 v18, 0xba000000, v17
	v_fmac_f32_e32 v21, 0xba000000, v17
	v_fmac_f32_e32 v20, 0xba000000, v17
	v_pk_mul_f32 v[20:21], v[16:17], v[20:21] op_sel_hi:[0,1]
	v_pk_mul_f32 v[18:19], v[16:17], v[18:19] op_sel_hi:[0,1]
	v_pk_fma_f32 v[18:19], v[72:73], v[18:19], v[76:77]
	v_pk_fma_f32 v[20:21], v[74:75], v[20:21], v[78:79]
	v_pk_fma_f32 v[12:13], v[18:19], s[62:63], v[12:13] op_sel_hi:[1,0,1]
	v_pk_fma_f32 v[14:15], v[20:21], s[62:63], v[14:15] op_sel_hi:[1,0,1]
	v_cvt_pk_bf16_f32 v18, v12, v13
	v_cmp_lt_i32_e64 s[4:5], 0, v247
	v_cvt_pk_bf16_f32 v19, v14, v15
	global_store_dwordx2 v[80:81], v[18:19], off
	v_add_f32_e32 v18, v12, v13
	v_add_f32_e32 v19, v14, v15
	v_add_f32_e32 v18, v18, v19
	v_pk_mul_f32 v[14:15], v[14:15], v[14:15]
	v_pk_mul_f32 v[12:13], v[12:13], v[12:13]
	v_add_f32_e32 v20, 0, v18
	v_pk_mov_b32 v[18:19], v[12:13], v[14:15] op_sel:[1,0]
	v_mov_b32_e32 v13, v15
	v_pk_add_f32 v[12:13], v[18:19], v[12:13]
	v_lshlrev_b32_e32 v14, 16, v86
	v_and_b32_e32 v15, 0xffff0000, v86
	v_lshlrev_b32_e32 v18, 16, v87
	v_and_b32_e32 v19, 0xffff0000, v87
	v_fmac_f32_e32 v15, 0xba000000, v17
	v_fmac_f32_e32 v14, 0xba000000, v17
	v_fmac_f32_e32 v19, 0xba000000, v17
	v_fmac_f32_e32 v18, 0xba000000, v17
	v_pk_mul_f32 v[18:19], v[16:17], v[18:19] op_sel_hi:[0,1]
	v_pk_mul_f32 v[14:15], v[16:17], v[14:15] op_sel_hi:[0,1]
	v_pk_fma_f32 v[14:15], v[64:65], v[14:15], v[68:69]
	v_pk_fma_f32 v[18:19], v[66:67], v[18:19], v[70:71]
	v_pk_fma_f32 v[8:9], v[14:15], s[62:63], v[8:9] op_sel_hi:[1,0,1]
	v_pk_fma_f32 v[10:11], v[18:19], s[62:63], v[10:11] op_sel_hi:[1,0,1]
	v_cvt_pk_bf16_f32 v14, v8, v9
	s_mov_b64 s[12:13], 0
	v_cvt_pk_bf16_f32 v15, v10, v11
	global_store_dwordx2 v[80:81], v[14:15], off offset:32
	v_add_f32_e32 v14, v8, v9
	v_add_f32_e32 v15, v10, v11
	v_add_f32_e32 v14, v14, v15
	v_pk_mul_f32 v[10:11], v[10:11], v[10:11]
	v_pk_mul_f32 v[8:9], v[8:9], v[8:9]
	v_add_f32_e32 v18, v20, v14
	v_pk_mov_b32 v[14:15], v[8:9], v[10:11] op_sel:[1,0]
	v_mov_b32_e32 v9, v11
	v_pk_add_f32 v[8:9], v[14:15], v[8:9]
	v_lshlrev_b32_e32 v10, 16, v84
	v_and_b32_e32 v11, 0xffff0000, v84
	v_lshlrev_b32_e32 v14, 16, v85
	v_and_b32_e32 v15, 0xffff0000, v85
	v_fmac_f32_e32 v11, 0xba000000, v17
	v_fmac_f32_e32 v10, 0xba000000, v17
	v_fmac_f32_e32 v15, 0xba000000, v17
	v_fmac_f32_e32 v14, 0xba000000, v17
	v_pk_mul_f32 v[14:15], v[16:17], v[14:15] op_sel_hi:[0,1]
	v_pk_mul_f32 v[10:11], v[16:17], v[10:11] op_sel_hi:[0,1]
	v_pk_fma_f32 v[10:11], v[56:57], v[10:11], v[60:61]
	v_pk_fma_f32 v[14:15], v[58:59], v[14:15], v[62:63]
	v_pk_fma_f32 v[4:5], v[10:11], s[62:63], v[4:5] op_sel_hi:[1,0,1]
	v_pk_fma_f32 v[6:7], v[14:15], s[62:63], v[6:7] op_sel_hi:[1,0,1]
	v_cvt_pk_bf16_f32 v10, v4, v5
	v_lshlrev_b32_e32 v14, 16, v83
	v_cvt_pk_bf16_f32 v11, v6, v7
	global_store_dwordx2 v[80:81], v[10:11], off offset:256
	v_add_f32_e32 v10, v4, v5
	v_add_f32_e32 v11, v6, v7
	v_add_f32_e32 v10, v10, v11
	v_add_f32_e32 v18, v18, v10
	v_lshlrev_b32_e32 v10, 16, v82
	v_and_b32_e32 v11, 0xffff0000, v82
	v_and_b32_e32 v15, 0xffff0000, v83
	v_fmac_f32_e32 v11, 0xba000000, v17
	v_fmac_f32_e32 v10, 0xba000000, v17
	v_fmac_f32_e32 v15, 0xba000000, v17
	v_fmac_f32_e32 v14, 0xba000000, v17
	v_pk_mul_f32 v[14:15], v[16:17], v[14:15] op_sel_hi:[0,1]
	v_pk_mul_f32 v[10:11], v[16:17], v[10:11] op_sel_hi:[0,1]
	v_pk_fma_f32 v[10:11], v[48:49], v[10:11], v[52:53]
	v_pk_fma_f32 v[14:15], v[50:51], v[14:15], v[54:55]
	v_pk_fma_f32 v[0:1], v[10:11], s[62:63], v[0:1] op_sel_hi:[1,0,1]
	v_pk_fma_f32 v[2:3], v[14:15], s[62:63], v[2:3] op_sel_hi:[1,0,1]
	v_cvt_pk_bf16_f32 v10, v0, v1
	v_mul_f32_e32 v14, v1, v1
	v_cvt_pk_bf16_f32 v11, v2, v3
	global_store_dwordx2 v[80:81], v[10:11], off offset:288
	v_add_f32_e32 v10, v0, v1
	v_add_f32_e32 v11, v2, v3
	v_add_f32_e32 v10, v10, v11
	v_mul_f32_e32 v11, v0, v0
	v_mul_f32_e32 v15, v2, v2
	v_mul_f32_e32 v16, v3, v3
	v_pk_add_f32 v[0:1], v[12:13], v[12:13] op_sel:[0,1] op_sel_hi:[1,0]
	v_pk_add_f32 v[2:3], v[8:9], v[8:9] op_sel:[0,1] op_sel_hi:[1,0]
	v_mov_b32_e32 v1, v11
	v_mov_b32_e32 v3, v14
	v_pk_add_f32 v[0:1], v[0:1], v[2:3]
	v_mul_f32_e32 v2, v5, v5
	v_pk_fma_f32 v[2:3], v[4:5], v[4:5], v[2:3] op_sel_hi:[1,1,0]
	v_mul_f32_e32 v4, v7, v7
	v_pk_fma_f32 v[4:5], v[6:7], v[6:7], v[4:5] op_sel_hi:[1,1,0]
	v_mov_b32_e32 v3, v15
	v_mov_b32_e32 v5, v16
	v_pk_add_f32 v[2:3], v[2:3], v[4:5]
	v_add_f32_e32 v10, v18, v10
	v_pk_add_f32 v[0:1], v[0:1], v[2:3]
	s_nop 0
	v_pk_add_f32 v[0:1], v[0:1], v[0:1] op_sel:[0,1] op_sel_hi:[1,0]
	s_nop 0
	v_mov_b32_e32 v1, v10
	s_nop 1
	v_permlane16_swap_b32_e32 v10, v1
	v_add_f32_e32 v4, v10, v1
	v_mov_b32_e32 v1, v0
	s_nop 1
	v_permlane16_swap_b32_e32 v0, v1
	v_add_f32_e32 v2, v0, v1
	v_mov_b32_e32 v5, v4
	v_mov_b32_e32 v3, v2
	s_nop 0
	v_permlane32_swap_b32_e32 v4, v5
	v_permlane32_swap_b32_e32 v2, v3
	s_and_saveexec_b64 s[14:15], s[4:5]
	s_xor_b64 s[4:5], exec, s[14:15]
	s_cbranch_execnz .LBB0_1273
	s_or_saveexec_b64 s[4:5], s[4:5]
	v_mov_b64_e32 v[0:1], 0x140000
	s_xor_b64 exec, exec, s[4:5]
	s_cbranch_execnz .LBB0_1274
